# v28 + one static s_setprio 1 for waves 4-7 inside the MLA K-loops
# speedup vs baseline: 1.0090x; 1.0090x over previous
.LBB0_974:
	s_andn2_saveexec_b64 s[2:3], s[48:49]
	s_cbranch_execz .LBB0_982
	v_subrev_u32_e32 v0, 36, v2
	s_movk_i32 s4, 0x1ff
	v_cmp_lt_u32_e32 vcc, s4, v0
	s_and_saveexec_b64 s[4:5], vcc
	s_xor_b64 s[4:5], exec, s[4:5]
	v_add_u32_e32 v2, 0xfffffddc, v2
	v_lshrrev_b32_e32 v2, 6, v2
	v_add_u32_e32 v3, 4, v2
	s_or_saveexec_b64 s[4:5], s[4:5]
	v_mov_b32_e32 v27, 0x800
	v_mov_b32_e32 v2, 15
	v_mov_b32_e32 v4, 4
	s_xor_b64 exec, exec, s[4:5]
	v_lshrrev_b32_e32 v3, 7, v0
	v_mov_b32_e32 v27, 0x1000
	v_mov_b32_e32 v2, 31
	v_mov_b32_e32 v4, 5
	s_or_b64 exec, exec, s[4:5]
	v_bfe_u32 v8, v0, v4, 2
	v_lshlrev_b32_e32 v4, 12, v3
	v_lshl_add_u32 v5, v3, 11, v161
	v_cmp_gt_u32_e32 vcc, 4, v3
	v_mul_u32_u24_e32 v3, 0x60, v8
	v_lshlrev_b32_e32 v119, 6, v8
	v_cndmask_b32_e32 v4, v5, v4, vcc
	v_mov_b32_e32 v5, v1
	v_lshlrev_b32_e32 v62, 1, v3
	v_lshlrev_b64 v[64:65], 9, v[4:5]
	v_mul_u32_u24_e32 v3, v119, v27
	v_mbcnt_lo_u32_b32 v5, -1, 0
	v_mbcnt_hi_u32_b32 v5, -1, v5
	v_lshlrev_b32_e32 v66, 1, v3
	v_or_b32_e32 v78, s8, v5
	v_mov_b64_e32 v[6:7], s[24:25]
	v_mul_hi_i32 v3, v78, s67
	v_lshrrev_b32_e32 v5, 31, v3
	v_ashrrev_i32_e32 v3, 1, v3
	v_add_u32_e32 v79, v3, v5
	v_mul_lo_u32 v3, v79, 12
	v_sub_u32_e32 v26, v78, v3
	v_add_u32_e32 v3, 0x100, v78
	v_mul_hi_i32 v5, v3, s67
	v_lshrrev_b32_e32 v8, 31, v5
	v_ashrrev_i32_e32 v5, 1, v5
	v_add_u32_e32 v80, v5, v8
	v_mul_lo_u32 v5, v80, 12
	v_sub_u32_e32 v52, v3, v5
	v_add_u32_e32 v3, 0x200, v78
	v_mov_b32_e32 v63, v1
	v_mad_u64_u32 v[6:7], s[4:5], v4, s63, v[6:7]
	v_lshlrev_b32_e32 v110, 3, v26
	v_mul_hi_i32 v5, v3, s67
	v_lshl_add_u64 v[48:49], v[6:7], 0, v[62:63]
	v_lshlrev_b32_e32 v112, 3, v52
	v_lshrrev_b32_e32 v8, 31, v5
	v_ashrrev_i32_e32 v5, 1, v5
	v_ashrrev_i32_e32 v111, 31, v110
	v_add_u32_e32 v81, v5, v8
	v_mad_i64_i32 v[8:9], s[4:5], v79, s63, v[48:49]
	v_lshlrev_b64 v[68:69], 1, v[110:111]
	v_ashrrev_i32_e32 v113, 31, v112
	v_lshl_add_u64 v[8:9], v[8:9], 0, v[68:69]
	v_mad_i64_i32 v[10:11], s[4:5], v80, s63, v[48:49]
	v_lshlrev_b64 v[70:71], 1, v[112:113]
	v_mul_lo_u32 v5, v81, 12
	v_lshl_add_u64 v[10:11], v[10:11], 0, v[70:71]
	global_load_dwordx4 v[28:31], v[8:9], off
	global_load_dwordx4 v[32:35], v[10:11], off
	v_sub_u32_e32 v53, v3, v5
	v_lshlrev_b32_e32 v114, 3, v53
	v_lshl_add_u64 v[6:7], s[26:27], 0, v[64:65]
	v_mov_b32_e32 v67, v1
	v_ashrrev_i32_e32 v82, 3, v78
	v_lshlrev_b32_e32 v3, 3, v78
	v_ashrrev_i32_e32 v115, 31, v114
	v_lshl_add_u64 v[6:7], v[6:7], 0, v[66:67]
	v_and_b32_e32 v3, 56, v3
	v_mad_i64_i32 v[8:9], s[4:5], v81, s63, v[48:49]
	v_lshlrev_b64 v[72:73], 1, v[114:115]
	v_mad_i64_i32 v[10:11], s[4:5], v82, v27, 0
	v_add_u32_e32 v83, 32, v82
	v_lshl_add_u64 v[8:9], v[8:9], 0, v[72:73]
	v_lshl_add_u64 v[10:11], v[10:11], 1, v[6:7]
	v_lshlrev_b32_e32 v124, 1, v3
	v_mov_b32_e32 v125, v1
	v_lshl_add_u64 v[50:51], v[10:11], 0, v[124:125]
	global_load_dwordx4 v[36:39], v[8:9], off
	global_load_dwordx4 v[40:43], v[50:51], off
	v_mad_i64_i32 v[8:9], s[4:5], v83, v27, 0
	v_lshl_add_u64 v[6:7], v[8:9], 1, v[6:7]
	v_lshl_add_u64 v[58:59], v[6:7], 0, v[124:125]
	global_load_dwordx4 v[44:47], v[58:59], off
	v_and_b32_e32 v0, v2, v0
	v_lshl_add_u32 v0, v0, 7, v4
	v_mov_b64_e32 v[2:3], s[10:11]
	v_ashrrev_i32_e32 v5, 1, v78
	v_mad_u64_u32 v[2:3], s[4:5], v0, s63, v[2:3]
	v_mad_u64_u32 v[74:75], s[4:5], v4, s63, 0
	v_and_b32_e32 v84, 15, v78
	v_bfe_u32 v4, v78, 4, 2
	v_and_b32_e32 v121, 0xffffffe0, v5
	v_lshl_add_u64 v[2:3], v[2:3], 0, v[62:63]
	v_or_b32_e32 v120, v121, v84
	v_lshlrev_b32_e32 v76, 4, v4
	v_mov_b32_e32 v77, v1
	v_mul_lo_u32 v54, v79, s68
	v_lshl_add_u64 v[2:3], v[2:3], 0, v[76:77]
	v_or_b32_e32 v6, 16, v120
	v_lshlrev_b32_e32 v143, 1, v54
	v_lshlrev_b32_e32 v26, 4, v26
	v_lshlrev_b32_e32 v118, 3, v4
	v_mad_i64_i32 v[4:5], s[4:5], v120, s63, v[2:3]
	v_mad_i64_i32 v[2:3], s[4:5], v6, s63, v[2:3]
	v_add3_u32 v26, s92, v143, v26
	global_load_dwordx4 v[22:25], v[4:5], off
	global_load_dwordx4 v[14:17], v[4:5], off offset:64
	global_load_dwordx4 v[6:9], v[4:5], off offset:128
	global_load_dwordx4 v[18:21], v[2:3], off
	global_load_dwordx4 v[10:13], v[2:3], off offset:64
	s_nop 0
	global_load_dwordx4 v[2:5], v[2:3], off offset:128
	s_waitcnt lgkmcnt(0)
	s_barrier
	v_lshrrev_b32_e32 v77, 6, v27
	v_mov_b32_e32 v126, 0
	s_mov_b32 s6, 0
	v_add_u32_e32 v151, -2, v77
	v_mov_b32_e32 v153, 0xf149f2ca
	v_mov_b32_e32 v113, 0xf149f2ca
	v_mov_b32_e32 v127, v126
	s_waitcnt vmcnt(0)
	ds_write_b128 v26, v[28:31]
	v_mul_lo_u32 v26, v80, s68
	v_lshlrev_b32_e32 v145, 1, v26
	v_lshlrev_b32_e32 v26, 4, v52
	v_add3_u32 v26, s92, v145, v26
	ds_write_b128 v26, v[32:35]
	v_mul_lo_u32 v26, v81, s68
	v_lshlrev_b32_e32 v147, 1, v26
	v_lshlrev_b32_e32 v26, 4, v53
	v_add3_u32 v26, s92, v147, v26
	v_lshl_add_u64 v[28:29], v[48:49], 0, s[36:37]
	v_mad_i64_i32 v[30:31], s[4:5], v79, s63, v[28:29]
	v_mad_i64_i32 v[32:33], s[4:5], v80, s63, v[28:29]
	v_mad_i64_i32 v[28:29], s[4:5], v81, s63, v[28:29]
	v_lshl_add_u64 v[30:31], v[30:31], 0, v[68:69]
	v_lshl_add_u64 v[28:29], v[28:29], 0, v[72:73]
	v_lshl_add_u64 v[32:33], v[32:33], 0, v[70:71]
	ds_write_b128 v26, v[36:39]
	v_mul_lo_u32 v26, v82, s65
	v_lshlrev_b32_e32 v149, 1, v26
	v_add3_u32 v26, s92, v149, v124
	ds_write_b128 v26, v[40:43] offset:13312
	ds_write_b128 v26, v[44:47] offset:17920
	global_load_dwordx4 v[54:57], v[30:31], off
	global_load_dwordx4 v[46:49], v[32:33], off
	global_load_dwordx4 v[42:45], v[28:29], off
	s_nop 0
	global_load_dwordx4 v[50:53], v[50:51], off offset:128
	s_nop 0
	global_load_dwordx4 v[58:61], v[58:59], off offset:128
	v_mul_u32_u24_e32 v28, 0x68, v84
	v_lshlrev_b32_e32 v111, 1, v28
	v_lshlrev_b32_e32 v28, 6, v84
	v_or_b32_e32 v29, 0x400, v28
	v_sub_u32_e32 v125, 0, v28
	v_sub_u32_e32 v137, 0, v29
	v_or_b32_e32 v29, 0x800, v28
	v_or_b32_e32 v28, 0xc00, v28
	v_sub_u32_e32 v141, 0, v28
	v_lshlrev_b32_e32 v28, 1, v83
	v_and_b32_e32 v30, 7, v78
	v_sub_u32_e32 v139, 0, v29
	v_mad_i64_i32 v[28:29], s[4:5], v28, v27, v[64:65]
	v_lshlrev_b32_e32 v30, 4, v30
	v_mov_b32_e32 v31, v1
	v_lshl_add_u64 v[28:29], v[28:29], 0, v[30:31]
	v_lshl_add_u64 v[28:29], v[28:29], 0, v[66:67]
	v_lshl_add_u64 v[116:117], v[28:29], 0, s[38:39]
	v_lshlrev_b32_e32 v28, 1, v82
	v_mad_i64_i32 v[28:29], s[4:5], v28, v27, v[64:65]
	v_lshl_add_u64 v[28:29], v[28:29], 0, v[30:31]
	v_lshl_add_u64 v[28:29], v[28:29], 0, v[66:67]
	v_lshl_add_u64 v[128:129], v[28:29], 0, s[38:39]
	v_mad_i64_i32 v[28:29], s[4:5], v81, s63, v[74:75]
	v_lshl_add_u64 v[28:29], v[28:29], 0, v[72:73]
	v_lshl_add_u64 v[28:29], v[28:29], 0, v[62:63]
	v_lshl_add_u64 v[130:131], v[28:29], 0, s[40:41]
	v_mad_i64_i32 v[28:29], s[4:5], v80, s63, v[74:75]
	v_lshl_add_u64 v[28:29], v[28:29], 0, v[70:71]
	v_lshl_add_u64 v[28:29], v[28:29], 0, v[62:63]
	v_lshl_add_u64 v[132:133], v[28:29], 0, s[40:41]
	v_mad_i64_i32 v[28:29], s[4:5], v79, s63, v[74:75]
	v_lshl_add_u64 v[28:29], v[28:29], 0, v[68:69]
	v_mov_b32_e32 v26, v1
	v_lshl_add_u64 v[28:29], v[28:29], 0, v[62:63]
	s_waitcnt lgkmcnt(0)
	s_barrier
	v_add3_u32 v123, s92, v76, v111
	v_lshl_add_u64 v[134:135], v[28:29], 0, s[40:41]
	s_mov_b64 s[4:5], 0
	v_mov_b32_e32 v27, v26
	v_mov_b32_e32 v28, v26
	v_mov_b32_e32 v29, v26
	v_mov_b32_e32 v30, v26
	v_mov_b32_e32 v31, v26
	v_mov_b32_e32 v32, v26
	v_mov_b32_e32 v33, v26
	v_mov_b32_e32 v34, v26
	v_mov_b32_e32 v35, v26
	v_mov_b32_e32 v36, v26
	v_mov_b32_e32 v37, v26
	v_mov_b32_e32 v38, v26
	v_mov_b32_e32 v39, v26
	v_mov_b32_e32 v40, v26
	v_mov_b32_e32 v41, v26
	v_mov_b32_e32 v62, v26
	v_mov_b32_e32 v63, v26
	v_mov_b32_e32 v64, v26
	v_mov_b32_e32 v65, v26
	v_mov_b32_e32 v66, v26
	v_mov_b32_e32 v67, v26
	v_mov_b32_e32 v68, v26
	v_mov_b32_e32 v69, v26
	v_mov_b32_e32 v70, v26
	v_mov_b32_e32 v71, v26
	v_mov_b32_e32 v72, v26
	v_mov_b32_e32 v73, v26
	v_mov_b32_e32 v74, v26
	v_mov_b32_e32 v75, v26
	v_mov_b32_e32 v76, v26
	v_mov_b32_e32 v77, v26
	v_readlane_b32 s98, v236, 62
	s_nop 3
	s_cmp_lt_u32 s98, 4
	s_cbranch_scc1 .Lprio_skip_0
	s_setprio 1
.Lprio_skip_0:
.LBB0_980:
	s_and_b32 s7, s6, 1
	s_mul_i32 s33, s7, 0x5800
	v_mov_b32_e32 v78, 0
	v_add_u32_e32 v138, s33, v123
	ds_read_b128 v[82:85], v138
	ds_read_b128 v[86:89], v138 offset:3328
	ds_read_b128 v[90:93], v138 offset:6656
	ds_read_b128 v[94:97], v138 offset:9984
	v_mov_b32_e32 v79, v78
	v_mov_b32_e32 v80, v78
	v_mov_b32_e32 v81, v78
	v_mov_b32_e32 v136, v153
	v_mov_b32_e32 v115, v113
	s_waitcnt lgkmcnt(0)
	v_mfma_f32_16x16x32_bf16 v[98:101], v[82:85], v[22:25], v[78:81]
	v_and_b32_e32 v148, 64, v170
	v_xor_b32_e32 v146, 16, v170
	v_add_u32_e32 v148, 64, v148
	v_mfma_f32_16x16x32_bf16 v[102:105], v[86:89], v[22:25], v[78:81]
	v_cmp_lt_i32_e32 vcc, v146, v148
	v_add_u32_e32 v140, 0xd00, v138
	v_add_u32_e32 v142, 0x1a00, v138
	v_mfma_f32_16x16x32_bf16 v[106:109], v[90:93], v[22:25], v[78:81]
	v_cndmask_b32_e32 v146, v170, v146, vcc
	v_lshlrev_b32_e32 v165, 2, v146
	v_add_u32_e32 v144, 0x2700, v138
	v_mfma_f32_16x16x32_bf16 v[152:155], v[94:97], v[22:25], v[78:81]
	s_xor_b32 s7, s7, 1
	s_mulk_i32 s7, 0x5800
	s_add_i32 s7, s92, s7
	v_mfma_f32_16x16x32_bf16 v[82:85], v[82:85], v[18:21], v[78:81]
	s_add_i32 s6, s6, 1
	v_mfma_f32_16x16x32_bf16 v[86:89], v[86:89], v[18:21], v[78:81]
	v_mfma_f32_16x16x32_bf16 v[90:93], v[90:93], v[18:21], v[78:81]
	v_mfma_f32_16x16x32_bf16 v[78:81], v[94:97], v[18:21], v[78:81]
	ds_read_b128 v[94:97], v138 offset:64
	ds_read_b128 v[166:169], v138 offset:3392
	ds_read_b128 v[172:175], v138 offset:6720
	ds_read_b128 v[176:179], v138 offset:10048
	s_waitcnt lgkmcnt(0)
	v_mfma_f32_16x16x32_bf16 v[98:101], v[94:97], v[14:17], v[98:101]
	v_mfma_f32_16x16x32_bf16 v[102:105], v[166:169], v[14:17], v[102:105]
	v_mfma_f32_16x16x32_bf16 v[180:183], v[172:175], v[14:17], v[106:109]
	v_mfma_f32_16x16x32_bf16 v[152:155], v[176:179], v[14:17], v[152:155]
	v_mfma_f32_16x16x32_bf16 v[86:89], v[166:169], v[10:13], v[86:89]
	v_mfma_f32_16x16x32_bf16 v[166:169], v[172:175], v[10:13], v[90:93]
	v_mfma_f32_16x16x32_bf16 v[78:81], v[176:179], v[10:13], v[78:81]
	s_nop 1
	ds_read_b128 v[90:93], v138 offset:128
	ds_read_b128 v[172:175], v138 offset:3456
	ds_read_b128 v[176:179], v138 offset:6784
	ds_read_b128 v[184:187], v138 offset:10112
	s_waitcnt lgkmcnt(0)
	v_mfma_f32_16x16x32_bf16 v[106:109], v[90:93], v[6:9], v[98:101]
	v_mfma_f32_16x16x32_bf16 v[102:105], v[172:175], v[6:9], v[102:105]
	v_mfma_f32_16x16x32_bf16 v[98:101], v[176:179], v[6:9], v[180:183]
	s_nop 5
	v_max3_f32 v113, v106, s70, v107
	v_max3_f32 v113, v113, v108, v109
	v_max3_f32 v113, v113, v102, v103
	v_mfma_f32_16x16x32_bf16 v[82:85], v[94:97], v[10:13], v[82:85]
	v_max3_f32 v113, v113, v104, v105
	v_max3_f32 v113, v113, v98, v99
	v_max3_f32 v113, v113, v100, v101
	v_mfma_f32_16x16x32_bf16 v[94:97], v[184:187], v[6:9], v[152:155]
	v_mfma_f32_16x16x32_bf16 v[90:93], v[90:93], v[2:5], v[82:85]
	v_mfma_f32_16x16x32_bf16 v[82:85], v[176:179], v[2:5], v[166:169]
	s_nop 5
	v_max3_f32 v113, v113, v94, v95
	v_max3_f32 v113, v113, v96, v97
	ds_bpermute_b32 v146, v165, v113
	v_mfma_f32_16x16x32_bf16 v[86:89], v[172:175], v[2:5], v[86:89]
	v_lshlrev_b32_e32 v167, 1, v112
	s_waitcnt lgkmcnt(0)
	v_max_f32_e32 v146, v146, v146
	v_max_f32_e32 v113, v113, v146
	v_xor_b32_e32 v146, 32, v170
	v_cmp_lt_i32_e32 vcc, v146, v148
	v_mfma_f32_16x16x32_bf16 v[78:81], v[184:187], v[2:5], v[78:81]
	s_nop 0
	v_cndmask_b32_e32 v146, v170, v146, vcc
	v_lshlrev_b32_e32 v166, 2, v146
	ds_bpermute_b32 v146, v166, v113
	v_cmp_eq_u32_e32 vcc, s6, v151
	s_or_b64 s[4:5], vcc, s[4:5]
	s_waitcnt lgkmcnt(0)
	v_max3_f32 v113, v115, v113, v146
	v_sub_f32_e32 v94, v94, v113
	v_exp_f32_e32 v200, v94
	v_sub_f32_e32 v94, v95, v113
	v_exp_f32_e32 v202, v94
	v_sub_f32_e32 v94, v96, v113
	v_exp_f32_e32 v204, v94
	v_sub_f32_e32 v94, v97, v113
	v_exp_f32_e32 v206, v94
	v_max3_f32 v94, v90, s70, v91
	v_max3_f32 v94, v94, v92, v93
	v_max3_f32 v94, v94, v86, v87
	v_max3_f32 v94, v94, v88, v89
	v_max3_f32 v94, v94, v82, v83
	v_max3_f32 v94, v94, v84, v85
	v_max3_f32 v94, v94, v78, v79
	v_max3_f32 v94, v94, v80, v81
	ds_bpermute_b32 v95, v165, v94
	v_sub_f32_e32 v102, v102, v113
	v_sub_f32_e32 v98, v98, v113
	v_exp_f32_e32 v184, v102
	v_sub_f32_e32 v102, v103, v113
	s_waitcnt lgkmcnt(0)
	v_max_f32_e32 v95, v95, v95
	v_max_f32_e32 v94, v94, v95
	ds_bpermute_b32 v95, v166, v94
	v_exp_f32_e32 v192, v98
	v_sub_f32_e32 v98, v99, v113
	v_exp_f32_e32 v186, v102
	v_sub_f32_e32 v102, v104, v113
	s_waitcnt lgkmcnt(0)
	v_max3_f32 v153, v136, v94, v95
	v_sub_f32_e32 v86, v86, v153
	v_sub_f32_e32 v82, v82, v153
	v_sub_f32_e32 v78, v78, v153
	v_exp_f32_e32 v194, v98
	v_sub_f32_e32 v98, v100, v113
	v_exp_f32_e32 v185, v86
	v_sub_f32_e32 v86, v87, v153
	v_exp_f32_e32 v193, v82
	v_sub_f32_e32 v82, v83, v153
	v_exp_f32_e32 v201, v78
	v_sub_f32_e32 v78, v79, v153
	v_exp_f32_e32 v188, v102
	v_sub_f32_e32 v102, v105, v113
	v_exp_f32_e32 v196, v98
	v_sub_f32_e32 v98, v101, v113
	v_sub_f32_e32 v94, v136, v153
	v_exp_f32_e32 v187, v86
	v_sub_f32_e32 v86, v88, v153
	v_exp_f32_e32 v195, v82
	v_sub_f32_e32 v82, v84, v153
	v_exp_f32_e32 v203, v78
	v_sub_f32_e32 v78, v80, v153
	v_exp_f32_e32 v190, v102
	v_exp_f32_e32 v198, v98
	v_exp_f32_e32 v189, v86
	v_sub_f32_e32 v86, v89, v153
	v_exp_f32_e32 v197, v82
	v_sub_f32_e32 v82, v85, v153
	v_exp_f32_e32 v205, v78
	v_sub_f32_e32 v78, v81, v153
	v_exp_f32_e32 v209, v94
	v_add_u32_e32 v94, v138, v125
	v_add_u32_e32 v98, v140, v137
	v_add_u32_e32 v102, v142, v139
	v_sub_f32_e32 v106, v106, v113
	v_exp_f32_e32 v191, v86
	v_exp_f32_e32 v199, v82
	v_exp_f32_e32 v207, v78
	ds_read_b128 v[78:81], v94 offset:13312
	ds_read_b128 v[82:85], v98 offset:13312
	ds_read_b128 v[86:89], v102 offset:13312
	v_exp_f32_e32 v154, v106
	v_sub_f32_e32 v106, v107, v113
	v_sub_f32_e32 v90, v90, v153
	v_exp_f32_e32 v168, v106
	v_sub_f32_e32 v106, v108, v113
	v_exp_f32_e32 v155, v90
	v_sub_f32_e32 v90, v91, v153
	v_sub_f32_e32 v115, v115, v113
	v_exp_f32_e32 v180, v106
	v_sub_f32_e32 v106, v109, v113
	v_exp_f32_e32 v169, v90
	v_exp_f32_e32 v182, v106
	v_exp_f32_e32 v208, v115
	v_sub_f32_e32 v90, v92, v153
	v_exp_f32_e32 v181, v90
	v_sub_f32_e32 v90, v93, v153
	v_exp_f32_e32 v183, v90
	v_add_u32_e32 v106, v144, v141
	v_cvt_pk_bf16_f32 v172, v154, v168
	v_cvt_pk_bf16_f32 v176, v155, v169
	v_pk_add_f32 v[154:155], v[154:155], 0 op_sel_hi:[1,0]
	ds_read_b128 v[90:93], v106 offset:13312
	ds_read_b128 v[94:97], v94 offset:13376
	ds_read_b128 v[98:101], v98 offset:13376
	ds_read_b128 v[102:105], v102 offset:13376
	ds_read_b128 v[106:109], v106 offset:13376
	v_cvt_pk_bf16_f32 v173, v180, v182
	v_cvt_pk_bf16_f32 v174, v184, v186
	v_pk_add_f32 v[154:155], v[168:169], v[154:155]
	v_pk_mul_f32 v[76:77], v[76:77], v[208:209] op_sel_hi:[1,0]
	v_pk_mul_f32 v[74:75], v[74:75], v[208:209] op_sel_hi:[1,0]
	v_pk_mul_f32 v[72:73], v[72:73], v[208:209] op_sel_hi:[1,0]
	v_pk_mul_f32 v[70:71], v[70:71], v[208:209] op_sel_hi:[1,0]
	v_pk_mul_f32 v[68:69], v[68:69], v[208:209] op_sel_hi:[1,0]
	v_pk_mul_f32 v[66:67], v[66:67], v[208:209] op_sel_hi:[1,0]
	v_pk_mul_f32 v[64:65], v[64:65], v[208:209] op_sel_hi:[1,0]
	v_pk_mul_f32 v[62:63], v[62:63], v[208:209] op_sel_hi:[1,0]
	v_cvt_pk_bf16_f32 v175, v188, v190
	v_pk_add_f32 v[154:155], v[180:181], v[154:155]
	v_mov_b32_e32 v136, v209
	s_waitcnt lgkmcnt(0)
	v_mfma_f32_16x16x32_bf16 v[74:77], v[78:81], v[172:175], v[74:77]
	v_add_f32_e64 v154, v182, v154
	v_add_f32_e64 v155, v183, v155
	v_cvt_pk_bf16_f32 v177, v181, v183
	v_cvt_pk_bf16_f32 v178, v185, v187
	v_mfma_f32_16x16x32_bf16 v[70:73], v[82:85], v[172:175], v[70:73]
	v_add_f32_e64 v154, v184, v154
	v_add_f32_e64 v155, v185, v155
	v_pk_mul_f32 v[40:41], v[40:41], v[136:137] op_sel_hi:[1,0]
	v_pk_mul_f32 v[38:39], v[38:39], v[136:137] op_sel_hi:[1,0]
	v_mfma_f32_16x16x32_bf16 v[66:69], v[86:89], v[172:175], v[66:69]
	v_cvt_pk_bf16_f32 v179, v189, v191
	v_pk_add_f32 v[154:155], v[186:187], v[154:155]
	v_lshlrev_b32_e32 v168, 1, v114
	v_mfma_f32_16x16x32_bf16 v[62:65], v[90:93], v[172:175], v[62:65]
	v_mul_f32_e64 v36, v36, v136
	v_mul_f32_e64 v37, v37, v136
	v_pk_mul_f32 v[34:35], v[34:35], v[136:137] op_sel_hi:[1,0]
	v_pk_mul_f32 v[32:33], v[32:33], v[136:137] op_sel_hi:[1,0]
	v_mfma_f32_16x16x32_bf16 v[38:41], v[78:81], v[176:179], v[38:41]
	v_cvt_pk_bf16_f32 v78, v192, v194
	v_cvt_pk_bf16_f32 v79, v196, v198
	v_cvt_pk_bf16_f32 v80, v200, v202
	v_cvt_pk_bf16_f32 v81, v204, v206
	v_pk_mul_f32 v[30:31], v[30:31], v[136:137] op_sel_hi:[1,0]
	v_pk_mul_f32 v[28:29], v[28:29], v[136:137] op_sel_hi:[1,0]
	v_mfma_f32_16x16x32_bf16 v[74:77], v[94:97], v[78:81], v[74:77]
	v_mul_f32_e64 v26, v26, v136
	v_mul_f32_e64 v27, v27, v136
	v_mfma_f32_16x16x32_bf16 v[70:73], v[98:101], v[78:81], v[70:73]
	v_mfma_f32_16x16x32_bf16 v[66:69], v[102:105], v[78:81], v[66:69]
	v_mfma_f32_16x16x32_bf16 v[62:65], v[106:109], v[78:81], v[62:65]
	v_add_f32_e64 v78, v188, v154
	v_add_f32_e64 v79, v189, v155
	v_lshlrev_b32_e32 v155, 1, v110
	v_pk_add_f32 v[78:79], v[190:191], v[78:79]
	v_mfma_f32_16x16x32_bf16 v[34:37], v[82:85], v[176:179], v[34:37]
	v_add_f32_e64 v78, v192, v78
	v_add_f32_e64 v79, v193, v79
	v_cvt_pk_bf16_f32 v82, v193, v195
	v_pk_add_f32 v[78:79], v[194:195], v[78:79]
	v_mfma_f32_16x16x32_bf16 v[30:33], v[86:89], v[176:179], v[30:33]
	v_add_f32_e64 v78, v196, v78
	v_add_f32_e64 v79, v197, v79
	v_cvt_pk_bf16_f32 v83, v197, v199
	v_pk_add_f32 v[78:79], v[198:199], v[78:79]
	v_mfma_f32_16x16x32_bf16 v[26:29], v[90:93], v[176:179], v[26:29]
	v_add_f32_e64 v78, v200, v78
	v_add_f32_e64 v79, v201, v79
	v_cvt_pk_bf16_f32 v84, v201, v203
	v_pk_add_f32 v[78:79], v[202:203], v[78:79]
	v_cvt_pk_bf16_f32 v85, v205, v207
	v_pk_add_f32 v[78:79], v[204:205], v[78:79]
	s_nop 0
	v_pk_add_f32 v[78:79], v[206:207], v[78:79]
	v_mfma_f32_16x16x32_bf16 v[38:41], v[94:97], v[82:85], v[38:41]
	v_fma_f32 v126, v126, v208, v78
	v_fma_f32 v127, v127, v209, v79
	v_add3_u32 v78, s7, v143, v155
	s_waitcnt vmcnt(0)
	ds_write_b128 v78, v[54:57]
	v_add3_u32 v54, s7, v145, v167
	ds_write_b128 v54, v[46:49]
	v_add3_u32 v46, s7, v147, v168
	ds_write_b128 v46, v[42:45]
	v_add3_u32 v42, s7, v149, v124
	ds_write_b128 v42, v[50:53] offset:13312
	ds_write_b128 v42, v[58:61] offset:17920
	v_lshl_add_u64 v[42:43], s[10:11], 0, v[134:135]
	v_lshl_add_u64 v[50:51], s[10:11], 0, v[128:129]
	global_load_dwordx4 v[54:57], v[42:43], off
	v_lshl_add_u64 v[58:59], s[10:11], 0, v[116:117]
	global_load_dwordx4 v[50:53], v[50:51], off
	v_lshl_add_u64 v[42:43], s[10:11], 0, v[132:133]
	global_load_dwordx4 v[46:49], v[42:43], off
	v_mfma_f32_16x16x32_bf16 v[34:37], v[98:101], v[82:85], v[34:37]
	global_load_dwordx4 v[58:61], v[58:59], off
	v_lshl_add_u64 v[42:43], s[10:11], 0, v[130:131]
	global_load_dwordx4 v[42:45], v[42:43], off
	v_mfma_f32_16x16x32_bf16 v[30:33], v[102:105], v[82:85], v[30:33]
	v_lshl_add_u64 v[116:117], v[116:117], 0, s[42:43]
	v_lshl_add_u64 v[128:129], v[128:129], 0, s[42:43]
	v_lshl_add_u64 v[130:131], v[130:131], 0, s[36:37]
	v_mfma_f32_16x16x32_bf16 v[26:29], v[106:109], v[82:85], v[26:29]
	v_lshl_add_u64 v[132:133], v[132:133], 0, s[36:37]
	v_lshl_add_u64 v[134:135], v[134:135], 0, s[36:37]
	s_waitcnt lgkmcnt(0)
	s_barrier
	s_andn2_b64 exec, exec, s[4:5]
	s_cbranch_execnz .LBB0_980
	s_setprio 0
	s_or_b64 exec, exec, s[4:5]
	v_and_b32_e32 v78, 1, v151
	v_mov_b32_e32 v169, s92
	v_mad_u32_u24 v79, v78, s69, v169
	v_lshlrev_b32_e32 v80, 1, v118
	v_mov_b32_e32 v78, v1
	v_add3_u32 v171, v79, v80, v111
	ds_read_b128 v[82:85], v171
	ds_read_b128 v[86:89], v171 offset:64
	ds_read_b128 v[94:97], v171 offset:3328
	ds_read_b128 v[98:101], v171 offset:128
	v_mov_b32_e32 v79, v78
	v_mov_b32_e32 v80, v78
	v_mov_b32_e32 v81, v78
	ds_read_b128 v[106:109], v171 offset:6656
	ds_read_b128 v[114:117], v171 offset:6720
	s_waitcnt lgkmcnt(0)
	v_mfma_f32_16x16x32_bf16 v[90:93], v[82:85], v[22:25], v[78:81]
	ds_read_b128 v[132:135], v171 offset:9984
	ds_read_b128 v[172:175], v171 offset:6784
	ds_read_b128 v[180:183], v171 offset:3392
	ds_read_b128 v[184:187], v171 offset:3456
	ds_read_b128 v[188:191], v171 offset:10048
	ds_read_b128 v[192:195], v171 offset:10112
	v_mfma_f32_16x16x32_bf16 v[102:105], v[94:97], v[22:25], v[78:81]
	v_add_u32_e32 v200, 0x2700, v171
	v_ashrrev_i32_e32 v121, 31, v121
	v_mfma_f32_16x16x32_bf16 v[128:131], v[106:109], v[22:25], v[78:81]
	v_mfma_f32_16x16x32_bf16 v[90:93], v[86:89], v[14:17], v[90:93]
	s_waitcnt lgkmcnt(0)
	v_mfma_f32_16x16x32_bf16 v[176:179], v[132:135], v[22:25], v[78:81]
	v_mfma_f32_16x16x32_bf16 v[102:105], v[180:183], v[14:17], v[102:105]
	v_mfma_f32_16x16x32_bf16 v[128:131], v[114:117], v[14:17], v[128:131]
	v_mfma_f32_16x16x32_bf16 v[90:93], v[98:101], v[6:9], v[90:93]
	v_mfma_f32_16x16x32_bf16 v[176:179], v[188:191], v[14:17], v[176:179]
	v_mfma_f32_16x16x32_bf16 v[102:105], v[184:187], v[6:9], v[102:105]
	s_nop 5
	v_max3_f32 v110, v90, s70, v91
	v_max3_f32 v110, v110, v92, v93
	v_mfma_f32_16x16x32_bf16 v[196:199], v[172:175], v[6:9], v[128:131]
	v_mfma_f32_16x16x32_bf16 v[176:179], v[192:195], v[6:9], v[176:179]
	v_max3_f32 v110, v110, v102, v103
	v_max3_f32 v110, v110, v104, v105
	s_nop 4
	v_max3_f32 v110, v110, v196, v197
	v_max3_f32 v110, v110, v198, v199
	v_mfma_f32_16x16x32_bf16 v[82:85], v[82:85], v[18:21], v[78:81]
	v_max3_f32 v110, v110, v176, v177
	v_max3_f32 v110, v110, v178, v179
	ds_bpermute_b32 v111, v165, v110
	v_mfma_f32_16x16x32_bf16 v[94:97], v[94:97], v[18:21], v[78:81]
	v_add_u32_e32 v129, 0xd00, v171
	v_add_u32_e32 v131, 0x1a00, v171
	s_waitcnt lgkmcnt(0)
	v_max_f32_e32 v111, v111, v111
	v_max_f32_e32 v110, v110, v111
	ds_bpermute_b32 v111, v166, v110
	v_mfma_f32_16x16x32_bf16 v[106:109], v[106:109], v[18:21], v[78:81]
	s_waitcnt lgkmcnt(0)
	v_max3_f32 v228, v113, v110, v111
	v_sub_f32_e32 v90, v90, v228
	v_exp_f32_e32 v229, v90
	v_sub_f32_e32 v90, v91, v228
	v_exp_f32_e32 v230, v90
	v_sub_f32_e32 v90, v92, v228
	v_exp_f32_e32 v148, v90
	v_sub_f32_e32 v90, v93, v228
	v_mfma_f32_16x16x32_bf16 v[78:81], v[132:135], v[18:21], v[78:81]
	v_exp_f32_e32 v130, v90
	v_sub_f32_e32 v90, v102, v228
	v_exp_f32_e32 v134, v90
	v_mfma_f32_16x16x32_bf16 v[82:85], v[86:89], v[10:13], v[82:85]
	v_sub_f32_e32 v86, v104, v228
	v_sub_f32_e32 v90, v103, v228
	v_exp_f32_e32 v128, v86
	v_mfma_f32_16x16x32_bf16 v[86:89], v[180:183], v[10:13], v[94:97]
	v_exp_f32_e32 v138, v90
	v_sub_f32_e32 v90, v105, v228
	v_exp_f32_e32 v132, v90
	v_mfma_f32_16x16x32_bf16 v[90:93], v[114:117], v[10:13], v[106:109]
	v_sub_f32_e32 v110, v113, v228
	v_exp_f32_e32 v216, v110
	v_sub_f32_e32 v94, v196, v228
	v_mfma_f32_16x16x32_bf16 v[78:81], v[188:191], v[10:13], v[78:81]
	v_exp_f32_e32 v136, v94
	v_sub_f32_e32 v94, v197, v228
	v_exp_f32_e32 v140, v94
	v_mfma_f32_16x16x32_bf16 v[180:183], v[98:101], v[2:5], v[82:85]
	v_sub_f32_e32 v94, v198, v228
	v_exp_f32_e32 v142, v94
	v_sub_f32_e32 v94, v199, v228
	v_mfma_f32_16x16x32_bf16 v[184:187], v[184:187], v[2:5], v[86:89]
	v_sub_f32_e32 v82, v176, v228
	v_exp_f32_e32 v146, v82
	v_sub_f32_e32 v82, v177, v228
	v_mfma_f32_16x16x32_bf16 v[114:117], v[172:175], v[2:5], v[90:93]
	v_exp_f32_e32 v150, v82
	v_sub_f32_e32 v82, v178, v228
	v_exp_f32_e32 v152, v82
	v_mfma_f32_16x16x32_bf16 v[110:113], v[192:195], v[2:5], v[78:81]
	v_sub_f32_e32 v82, v179, v228
	v_exp_f32_e32 v144, v94
	v_exp_f32_e32 v154, v82
	v_max3_f32 v78, v180, s70, v181
	v_max3_f32 v78, v78, v182, v183
	v_max3_f32 v78, v78, v184, v185
	v_max3_f32 v78, v78, v186, v187
	v_add_u32_e32 v79, v129, v137
	v_bitop3_b32 v129, v151, 1, v151 bitop3:0xc
	v_max3_f32 v78, v78, v114, v115
	v_mad_u32_u24 v129, v129, s69, v169
	v_max3_f32 v133, v78, v116, v117
	v_add_u32_e32 v78, v171, v125
	v_add_u32_e32 v80, v131, v139
	v_add_u32_e32 v81, v200, v141
	v_add3_u32 v131, v129, v143, v155
	ds_read_b128 v[106:109], v78 offset:13312
	ds_read_b128 v[90:93], v78 offset:13376
	ds_read_b128 v[102:105], v79 offset:13312
	ds_read_b128 v[86:89], v79 offset:13376
	ds_read_b128 v[98:101], v80 offset:13312
	ds_read_b128 v[82:85], v80 offset:13376
	ds_read_b128 v[94:97], v81 offset:13312
	ds_read_b128 v[78:81], v81 offset:13376
	s_waitcnt vmcnt(0)
	ds_write_b128 v131, v[54:57]
	v_add3_u32 v54, v129, v145, v167
	ds_write_b128 v54, v[46:49]
	v_add3_u32 v46, v129, v147, v168
	ds_write_b128 v46, v[42:45]
	v_add3_u32 v42, v129, v149, v124
	ds_write_b128 v42, v[50:53] offset:13312
	ds_write_b128 v42, v[58:61] offset:17920
	v_max3_f32 v42, v133, v110, v111
	v_max3_f32 v42, v42, v112, v113
	ds_bpermute_b32 v43, v165, v42
	v_mov_b32_e32 v46, v1
	s_waitcnt lgkmcnt(0)
	s_barrier
	ds_read_b128 v[50:53], v123 offset:22528
	ds_read_b128 v[54:57], v123 offset:25856
	v_max_f32_e32 v43, v43, v43
	v_pk_mul_f32 v[44:45], v[68:69], v[216:217] op_sel_hi:[1,0]
	v_max_f32_e32 v68, v42, v43
	ds_bpermute_b32 v69, v166, v68
	ds_read_b128 v[58:61], v123 offset:29184
	ds_read_b128 v[172:175], v123 offset:22592
	ds_read_b128 v[188:191], v123 offset:32512
	ds_read_b128 v[192:195], v123 offset:22656
	ds_read_b128 v[200:203], v123 offset:29248
	ds_read_b128 v[224:227], v123 offset:25920
	v_mov_b32_e32 v47, v46
	v_mov_b32_e32 v48, v46
	v_mov_b32_e32 v49, v46
	v_mul_f32_e32 v126, v126, v216
	v_pk_mul_f32 v[76:77], v[76:77], v[216:217] op_sel_hi:[1,0]
	s_waitcnt lgkmcnt(8)
	v_mfma_f32_16x16x32_bf16 v[176:179], v[50:53], v[22:25], v[46:49]
	v_mul_f32_e64 v74, v74, v216
	v_mul_f32_e64 v75, v75, v216
	v_pk_mul_f32 v[72:73], v[72:73], v[216:217] op_sel_hi:[1,0]
	v_pk_mul_f32 v[70:71], v[70:71], v[216:217] op_sel_hi:[1,0]
	s_waitcnt lgkmcnt(7)
	v_mfma_f32_16x16x32_bf16 v[196:199], v[54:57], v[22:25], v[46:49]
	v_mul_f32_e64 v42, v66, v216
	v_mul_f32_e64 v43, v67, v216
	ds_read_b128 v[208:211], v123 offset:29312
	s_waitcnt lgkmcnt(6)
	v_mfma_f32_16x16x32_bf16 v[204:207], v[58:61], v[22:25], v[46:49]
	s_waitcnt lgkmcnt(4)
	v_mfma_f32_16x16x32_bf16 v[212:215], v[188:191], v[22:25], v[46:49]
	v_mul_f32_e64 v24, v64, v216
	v_mul_f32_e64 v25, v65, v216
	v_pk_mul_f32 v[22:23], v[62:63], v[216:217] op_sel_hi:[1,0]
	v_mfma_f32_16x16x32_bf16 v[62:65], v[50:53], v[18:21], v[46:49]
	v_max3_f32 v51, v153, v68, v69
	v_sub_f32_e32 v50, v180, v51
	v_sub_f32_e32 v52, v185, v51
	v_mfma_f32_16x16x32_bf16 v[216:219], v[54:57], v[18:21], v[46:49]
	v_exp_f32_e32 v55, v50
	v_sub_f32_e32 v50, v181, v51
	v_exp_f32_e32 v57, v50
	v_mfma_f32_16x16x32_bf16 v[220:223], v[58:61], v[18:21], v[46:49]
	v_sub_f32_e32 v50, v182, v51
	v_exp_f32_e32 v66, v52
	v_sub_f32_e32 v52, v186, v51
	v_mfma_f32_16x16x32_bf16 v[18:21], v[188:191], v[18:21], v[46:49]
	v_exp_f32_e32 v68, v52
	v_sub_f32_e32 v52, v187, v51
	v_sub_f32_e32 v53, v153, v51
	v_sub_f32_e32 v46, v183, v51
	v_exp_f32_e32 v54, v46
	v_sub_f32_e32 v46, v184, v51
	v_exp_f32_e32 v58, v46
	ds_read_b128 v[46:49], v123 offset:32576
	ds_read_b128 v[180:183], v123 offset:25984
	v_mfma_f32_16x16x32_bf16 v[176:179], v[172:175], v[14:17], v[176:179]
	ds_read_b128 v[184:187], v123 offset:32640
	v_exp_f32_e32 v50, v50
	v_exp_f32_e32 v52, v52
	s_waitcnt lgkmcnt(4)
	v_mfma_f32_16x16x32_bf16 v[188:191], v[224:227], v[14:17], v[196:199]
	v_mfma_f32_16x16x32_bf16 v[196:199], v[200:203], v[14:17], v[204:207]
	s_waitcnt lgkmcnt(2)
	v_mfma_f32_16x16x32_bf16 v[204:207], v[46:49], v[14:17], v[212:215]
	v_sub_f32_e32 v14, v114, v51
	v_exp_f32_e32 v56, v14
	v_sub_f32_e32 v14, v115, v51
	v_exp_f32_e32 v60, v14
	v_sub_f32_e32 v14, v116, v51
	v_mfma_f32_16x16x32_bf16 v[176:179], v[192:195], v[6:9], v[176:179]
	v_mfma_f32_16x16x32_bf16 v[172:175], v[172:175], v[10:13], v[62:65]
	s_nop 2
	v_exp_f32_e32 v62, v14
	v_sub_f32_e32 v14, v117, v51
	v_exp_f32_e32 v64, v14
	v_sub_f32_e32 v14, v110, v51
	s_waitcnt lgkmcnt(1)
	v_mfma_f32_16x16x32_bf16 v[188:191], v[180:183], v[6:9], v[188:191]
	v_exp_f32_e32 v110, v14
	v_sub_f32_e32 v14, v111, v51
	v_exp_f32_e32 v114, v14
	v_mfma_f32_16x16x32_bf16 v[212:215], v[224:227], v[10:13], v[216:219]
	v_mfma_f32_16x16x32_bf16 v[200:203], v[200:203], v[10:13], v[220:223]
	v_mfma_f32_16x16x32_bf16 v[16:19], v[46:49], v[10:13], v[18:21]
	v_sub_f32_e32 v10, v112, v51
	v_exp_f32_e32 v48, v10
	v_sub_f32_e32 v10, v113, v51
	v_mfma_f32_16x16x32_bf16 v[12:15], v[208:211], v[6:9], v[196:199]
	v_max3_f32 v21, v176, s70, v177
	v_max3_f32 v21, v21, v178, v179
	v_exp_f32_e32 v20, v10
	s_waitcnt lgkmcnt(0)
	v_mfma_f32_16x16x32_bf16 v[8:11], v[184:187], v[6:9], v[204:207]
	v_max3_f32 v21, v21, v188, v189
	v_max3_f32 v21, v21, v190, v191
	v_exp_f32_e32 v112, v53
	v_max3_f32 v21, v21, v12, v13
	v_max3_f32 v21, v21, v14, v15
	s_nop 2
	v_max3_f32 v21, v21, v8, v9
	v_max3_f32 v21, v21, v10, v11
	v_pk_mul_f32 v[196:197], v[30:31], v[112:113] op_sel_hi:[1,0]
	ds_bpermute_b32 v31, v165, v21
	v_add_f32_e32 v7, 0, v229
	v_mfma_f32_16x16x32_bf16 v[172:175], v[192:195], v[2:5], v[172:175]
	v_add_f32_e32 v30, v230, v7
	v_add_f32_e32 v7, 0, v55
	v_pk_mul_f32 v[198:199], v[32:33], v[112:113] op_sel_hi:[1,0]
	v_add_f32_e32 v32, v57, v7
	s_waitcnt lgkmcnt(0)
	v_max_f32_e32 v7, v31, v31
	v_mfma_f32_16x16x32_bf16 v[180:183], v[180:183], v[2:5], v[212:215]
	v_max_f32_e32 v7, v21, v7
	ds_bpermute_b32 v21, v166, v7
	v_pk_mul_f32 v[40:41], v[40:41], v[112:113] op_sel_hi:[1,0]
	v_mfma_f32_16x16x32_bf16 v[200:203], v[208:211], v[2:5], v[200:203]
	v_mul_f32_e64 v38, v38, v112
	v_mul_f32_e64 v39, v39, v112
	v_pk_mul_f32 v[36:37], v[36:37], v[112:113] op_sel_hi:[1,0]
	v_pk_mul_f32 v[34:35], v[34:35], v[112:113] op_sel_hi:[1,0]
	v_mfma_f32_16x16x32_bf16 v[2:5], v[184:187], v[2:5], v[16:19]
	v_mul_f32_e64 v28, v28, v112
	v_mul_f32_e64 v29, v29, v112
	v_pk_mul_f32 v[26:27], v[26:27], v[112:113] op_sel_hi:[1,0]
	s_waitcnt lgkmcnt(0)
	v_max3_f32 v113, v228, v7, v21
	v_max3_f32 v16, v172, s70, v173
	v_max3_f32 v16, v16, v174, v175
	v_max3_f32 v16, v16, v180, v181
	v_max3_f32 v16, v16, v182, v183
	v_max3_f32 v16, v16, v200, v201
	v_sub_f32_e32 v7, v176, v113
	v_max3_f32 v16, v16, v202, v203
	v_exp_f32_e32 v149, v7
	v_sub_f32_e32 v7, v177, v113
	v_max3_f32 v16, v16, v2, v3
	v_exp_f32_e32 v131, v7
	v_sub_f32_e32 v7, v178, v113
	v_max3_f32 v16, v16, v4, v5
	v_exp_f32_e32 v135, v7
	v_sub_f32_e32 v7, v179, v113
	ds_bpermute_b32 v17, v165, v16
	v_add_u32_e32 v33, v123, v139
	v_exp_f32_e32 v139, v7
	v_sub_f32_e32 v7, v188, v113
	v_exp_f32_e32 v129, v7
	v_sub_f32_e32 v7, v189, v113
	v_exp_f32_e32 v133, v7
	v_sub_f32_e32 v7, v190, v113
	v_add_u32_e32 v31, v123, v137
	v_exp_f32_e32 v137, v7
	v_sub_f32_e32 v7, v191, v113
	v_mul_f32_e32 v46, v127, v112
	v_add_u32_e32 v112, v123, v141
	v_exp_f32_e32 v141, v7
	v_sub_f32_e32 v7, v12, v113
	s_waitcnt lgkmcnt(0)
	v_max_f32_e32 v12, v17, v17
	v_max_f32_e32 v12, v16, v12
	ds_bpermute_b32 v16, v166, v12
	v_exp_f32_e32 v143, v7
	v_sub_f32_e32 v7, v13, v113
	v_exp_f32_e32 v145, v7
	v_sub_f32_e32 v7, v14, v113
	s_waitcnt lgkmcnt(0)
	v_max3_f32 v12, v51, v12, v16
	v_sub_f32_e32 v14, v172, v12
	v_sub_f32_e32 v13, v51, v12
	v_exp_f32_e32 v51, v14
	v_sub_f32_e32 v14, v173, v12
	v_cvt_pk_bf16_f32 v192, v55, v57
	v_exp_f32_e32 v55, v14
	v_sub_f32_e32 v14, v174, v12
	v_exp_f32_e32 v59, v14
	v_sub_f32_e32 v14, v175, v12
	v_exp_f32_e32 v67, v14
	v_sub_f32_e32 v14, v180, v12
	v_exp_f32_e32 v69, v14
	v_sub_f32_e32 v14, v181, v12
	v_exp_f32_e32 v53, v14
	v_sub_f32_e32 v14, v182, v12
	v_exp_f32_e32 v57, v14
	v_sub_f32_e32 v14, v183, v12
	v_exp_f32_e32 v61, v14
	v_sub_f32_e32 v14, v200, v12
	v_exp_f32_e32 v63, v14
	v_sub_f32_e32 v14, v201, v12
	v_sub_f32_e32 v2, v2, v12
	v_exp_f32_e32 v65, v14
	v_sub_f32_e32 v14, v202, v12
	v_exp_f32_e32 v49, v2
	v_sub_f32_e32 v2, v3, v12
	v_exp_f32_e32 v111, v14
	v_cvt_pk_bf16_f32 v193, v50, v54
	v_cvt_pk_bf16_f32 v194, v58, v66
	v_cvt_pk_bf16_f32 v195, v68, v52
	v_sub_f32_e32 v14, v203, v12
	v_exp_f32_e32 v21, v2
	v_sub_f32_e32 v2, v4, v12
	v_sub_f32_e32 v12, v5, v12
	v_mfma_f32_16x16x32_bf16 v[16:19], v[106:109], v[192:195], v[38:41]
	v_exp_f32_e32 v47, v2
	ds_read_b128 v[176:179], v31 offset:39168
	ds_read_b128 v[180:183], v33 offset:42496
	ds_read_b128 v[184:187], v112 offset:45824
	v_exp_f32_e32 v115, v14
	v_mfma_f32_16x16x32_bf16 v[36:39], v[102:105], v[192:195], v[34:37]
	v_exp_f32_e32 v147, v7
	v_sub_f32_e32 v7, v15, v113
	v_exp_f32_e32 v151, v7
	v_exp_f32_e32 v35, v12
	v_add_u32_e32 v12, v123, v125
	v_mfma_f32_16x16x32_bf16 v[172:175], v[98:101], v[192:195], v[196:199]
	v_exp_f32_e32 v34, v13
	v_sub_f32_e32 v7, v8, v113
	v_exp_f32_e32 v153, v7
	v_mfma_f32_16x16x32_bf16 v[2:5], v[94:97], v[192:195], v[26:29]
	ds_read_b128 v[188:191], v12 offset:35840
	ds_read_b128 v[192:195], v12 offset:35904
	ds_read_b128 v[200:203], v31 offset:39232
	ds_read_b128 v[204:207], v33 offset:42560
	v_mov_b32_e32 v33, v1
	v_pk_add_f32 v[32:33], v[50:51], v[32:33]
	v_cvt_pk_bf16_f32 v26, v56, v60
	v_pk_add_f32 v[32:33], v[54:55], v[32:33]
	v_cvt_pk_bf16_f32 v27, v62, v64
	v_pk_add_f32 v[32:33], v[58:59], v[32:33]
	v_cvt_pk_bf16_f32 v28, v110, v114
	v_pk_add_f32 v[32:33], v[66:67], v[32:33]
	v_cvt_pk_bf16_f32 v29, v48, v20
	v_pk_add_f32 v[32:33], v[68:69], v[32:33]
	v_sub_f32_e32 v7, v9, v113
	v_pk_add_f32 v[32:33], v[52:53], v[32:33]
	v_mfma_f32_16x16x32_bf16 v[36:39], v[86:89], v[26:29], v[36:39]
	v_add_f32_e64 v32, v56, v32
	v_add_f32_e64 v33, v57, v33
	v_cvt_pk_bf16_f32 v196, v51, v55
	v_pk_add_f32 v[32:33], v[60:61], v[32:33]
	v_mfma_f32_16x16x32_bf16 v[16:19], v[90:93], v[26:29], v[16:19]
	v_add_f32_e64 v32, v62, v32
	v_add_f32_e64 v33, v63, v33
	v_cvt_pk_bf16_f32 v197, v59, v67
	v_pk_add_f32 v[32:33], v[64:65], v[32:33]
	v_mfma_f32_16x16x32_bf16 v[172:175], v[82:85], v[26:29], v[172:175]
	v_cvt_pk_bf16_f32 v198, v69, v53
	v_cvt_pk_bf16_f32 v199, v57, v61
	v_exp_f32_e32 v155, v7
	v_mfma_f32_16x16x32_bf16 v[2:5], v[78:81], v[26:29], v[2:5]
	v_mul_f32_e64 v28, v38, v34
	v_mul_f32_e64 v29, v39, v34
	v_pk_mul_f32 v[26:27], v[36:37], v[34:35] op_sel_hi:[1,0]
	v_sub_f32_e32 v7, v10, v113
	v_pk_add_f32 v[32:33], v[110:111], v[32:33]
	v_cvt_pk_bf16_f32 v6, v229, v230
	v_pk_mul_f32 v[18:19], v[18:19], v[34:35] op_sel_hi:[1,0]
	v_pk_mul_f32 v[16:17], v[16:17], v[34:35] op_sel_hi:[1,0]
	s_waitcnt lgkmcnt(6)
	v_mfma_f32_16x16x32_bf16 v[36:39], v[176:179], v[196:199], v[26:29]
	v_mul_f32_e64 v4, v4, v34
	v_mul_f32_e64 v5, v5, v34
	v_pk_mul_f32 v[2:3], v[2:3], v[34:35] op_sel_hi:[1,0]
	v_exp_f32_e32 v127, v7
	v_pk_mul_f32 v[28:29], v[174:175], v[34:35] op_sel_hi:[1,0]
	v_pk_mul_f32 v[26:27], v[172:173], v[34:35] op_sel_hi:[1,0]
	v_cvt_pk_bf16_f32 v7, v148, v130
	v_cvt_pk_bf16_f32 v8, v134, v138
	v_cvt_pk_bf16_f32 v9, v128, v132
	v_pk_add_f32 v[32:33], v[114:115], v[32:33]
	v_mov_b32_e32 v31, v1
	s_waitcnt lgkmcnt(3)
	v_mfma_f32_16x16x32_bf16 v[16:19], v[188:191], v[196:199], v[16:19]
	v_sub_f32_e32 v10, v11, v113
	v_sub_f32_e32 v116, v228, v113
	v_exp_f32_e32 v11, v10
	v_mfma_f32_16x16x32_bf16 v[172:175], v[180:183], v[196:199], v[26:29]
	v_exp_f32_e32 v10, v116
	ds_read_b128 v[208:211], v112 offset:45888
	v_cvt_pk_bf16_f32 v54, v149, v131
	v_mfma_f32_16x16x32_bf16 v[2:5], v[184:187], v[196:199], v[2:5]
	v_cvt_pk_bf16_f32 v198, v49, v21
	v_cvt_pk_bf16_f32 v196, v63, v65
	v_cvt_pk_bf16_f32 v197, v111, v115
	v_mfma_f32_16x16x32_bf16 v[40:43], v[98:101], v[6:9], v[42:45]
	v_cvt_pk_bf16_f32 v199, v47, v35
	v_cvt_pk_bf16_f32 v55, v135, v139
	v_cvt_pk_bf16_f32 v56, v129, v133
	v_pk_add_f32 v[44:45], v[48:49], v[32:33]
	v_pk_add_f32 v[48:49], v[148:149], v[30:31]
	s_waitcnt lgkmcnt(3)
	v_mfma_f32_16x16x32_bf16 v[26:29], v[192:195], v[196:199], v[16:19]
	v_add_f32_e64 v48, v130, v48
	v_add_f32_e64 v49, v131, v49
	v_cvt_pk_bf16_f32 v33, v127, v11
	v_pk_add_f32 v[48:49], v[134:135], v[48:49]
	s_waitcnt lgkmcnt(2)
	v_mfma_f32_16x16x32_bf16 v[16:19], v[200:203], v[196:199], v[36:39]
	v_add_f32_e64 v48, v138, v48
	v_add_f32_e64 v49, v139, v49
	v_cvt_pk_bf16_f32 v57, v137, v141
	v_pk_add_f32 v[48:49], v[128:129], v[48:49]
	v_mfma_f32_16x16x32_bf16 v[36:39], v[106:109], v[6:9], v[74:77]
	v_add_f32_e64 v48, v132, v48
	v_add_f32_e64 v49, v133, v49
	v_cvt_pk_bf16_f32 v30, v143, v145
	v_pk_add_f32 v[48:49], v[136:137], v[48:49]
	v_mfma_f32_16x16x32_bf16 v[70:73], v[102:105], v[6:9], v[70:73]
	v_add_f32_e64 v48, v140, v48
	v_add_f32_e64 v49, v141, v49
	v_cvt_pk_bf16_f32 v31, v147, v151
	v_pk_add_f32 v[48:49], v[142:143], v[48:49]
	v_mfma_f32_16x16x32_bf16 v[6:9], v[94:97], v[6:9], v[22:25]
	v_add_f32_e64 v48, v144, v48
	v_add_f32_e64 v49, v145, v49
	v_cvt_pk_bf16_f32 v32, v153, v155
	v_pk_add_f32 v[48:49], v[146:147], v[48:49]
	v_cvt_pk_bf16_f32 v22, v136, v140
	v_pk_add_f32 v[48:49], v[150:151], v[48:49]
	v_cvt_pk_bf16_f32 v23, v142, v144
	v_pk_add_f32 v[48:49], v[152:153], v[48:49]
	v_cvt_pk_bf16_f32 v24, v146, v150
	v_pk_add_f32 v[48:49], v[154:155], v[48:49]
	v_cvt_pk_bf16_f32 v25, v152, v154
	v_pk_add_f32 v[48:49], v[126:127], v[48:49]
	s_waitcnt lgkmcnt(0)
	v_add_f32_e32 v49, v49, v11
	v_mfma_f32_16x16x32_bf16 v[36:39], v[90:93], v[22:25], v[36:39]
	v_fmac_f32_e32 v49, v48, v10
	ds_bpermute_b32 v48, v165, v49
	s_barrier
	v_mfma_f32_16x16x32_bf16 v[50:53], v[86:89], v[22:25], v[70:73]
	s_waitcnt lgkmcnt(0)
	v_mfma_f32_16x16x32_bf16 v[40:43], v[82:85], v[22:25], v[40:43]
	v_mfma_f32_16x16x32_bf16 v[6:9], v[78:81], v[22:25], v[6:9]
	s_nop 0
	v_mul_f32_e64 v24, v38, v10
	v_mul_f32_e64 v25, v39, v10
	v_pk_mul_f32 v[22:23], v[36:37], v[10:11] op_sel_hi:[1,0]
	s_nop 0
	v_pk_mul_f32 v[38:39], v[52:53], v[10:11] op_sel_hi:[1,0]
	v_pk_mul_f32 v[36:37], v[50:51], v[10:11] op_sel_hi:[1,0]
	v_pk_mul_f32 v[42:43], v[42:43], v[10:11] op_sel_hi:[1,0]
	v_pk_mul_f32 v[40:41], v[40:41], v[10:11] op_sel_hi:[1,0]
	v_pk_mul_f32 v[8:9], v[8:9], v[10:11] op_sel_hi:[1,0]
	v_pk_mul_f32 v[6:7], v[6:7], v[10:11] op_sel_hi:[1,0]
	v_pk_add_f32 v[10:11], v[20:21], v[44:45]
	v_mfma_f32_16x16x32_bf16 v[22:25], v[188:191], v[54:57], v[22:25]
	v_add_f32_e64 v10, v46, v10
	v_add_f32_e64 v11, v47, v11
	v_add_f32_e32 v21, v11, v35
	v_add_f32_e32 v11, v49, v48
	ds_bpermute_b32 v20, v166, v11
	v_mfma_f32_16x16x32_bf16 v[36:39], v[176:179], v[54:57], v[36:39]
	v_fmac_f32_e32 v21, v10, v34
	s_waitcnt lgkmcnt(0)
	v_add_f32_e32 v20, v11, v20
	v_mfma_f32_16x16x32_bf16 v[40:43], v[180:183], v[54:57], v[40:43]
	v_lshl_add_u64 v[10:11], v[120:121], 0, v[0:1]
	v_mfma_f32_16x16x32_bf16 v[6:9], v[184:187], v[54:57], v[6:9]
	v_mfma_f32_16x16x32_bf16 v[22:25], v[192:195], v[30:33], v[22:25]
	v_mfma_f32_16x16x32_bf16 v[36:39], v[200:203], v[30:33], v[36:39]
	v_mfma_f32_16x16x32_bf16 v[40:43], v[204:207], v[30:33], v[40:43]
	v_mfma_f32_16x16x32_bf16 v[6:9], v[208:211], v[30:33], v[6:9]
	v_div_scale_f32 v30, s[4:5], v20, v20, 1.0
	v_rcp_f32_e32 v31, v30
	v_mfma_f32_16x16x32_bf16 v[12:15], v[204:207], v[196:199], v[172:175]
	v_fma_f32 v0, -v30, v31, 1.0
	v_fmac_f32_e32 v31, v0, v31
	v_div_scale_f32 v0, vcc, 1.0, v20, 1.0
	v_mul_f32_e32 v32, v0, v31
	v_fma_f32 v33, -v30, v32, v0
	v_fmac_f32_e32 v32, v33, v31
	v_fma_f32 v0, -v30, v32, v0
	v_div_fmas_f32 v0, v0, v31, v32
	v_mov_b64_e32 v[30:31], s[10:11]
	v_mad_u64_u32 v[30:31], s[4:5], v10, s52, v[30:31]
	v_div_fixup_f32 v20, v0, v20, 1.0
	v_mad_i32_i24 v31, v11, s52, v31
	v_lshlrev_b32_e32 v0, 1, v119
	v_mov_b32_e32 v119, v1
	v_lshl_add_u64 v[10:11], v[30:31], 0, v[0:1]
	v_lshl_add_u64 v[10:11], v[10:11], 0, v[118:119]
	s_mov_b64 s[4:5], 0xa000c00
	ds_bpermute_b32 v0, v165, v21
	v_lshl_add_u64 v[30:31], v[10:11], 0, s[4:5]
	v_pk_mul_f32 v[22:23], v[22:23], v[20:21] op_sel_hi:[1,0]
	v_pk_mul_f32 v[24:25], v[24:25], v[20:21] op_sel_hi:[1,0]
	s_mov_b32 s4, 0xa000000
	v_cvt_pk_bf16_f32 v22, v22, v23
	v_cvt_pk_bf16_f32 v23, v24, v25
	v_add_co_u32_e32 v24, vcc, s4, v10
	s_waitcnt lgkmcnt(0)
	v_add_f32_e32 v0, v21, v0
	v_addc_co_u32_e32 v25, vcc, 0, v11, vcc
	global_store_dwordx2 v[24:25], v[22:23], off offset:3072
	v_pk_mul_f32 v[22:23], v[36:37], v[20:21] op_sel_hi:[1,0]
	v_pk_mul_f32 v[24:25], v[38:39], v[20:21] op_sel_hi:[1,0]
	v_cvt_pk_bf16_f32 v22, v22, v23
	v_cvt_pk_bf16_f32 v23, v24, v25
	global_store_dwordx2 v[30:31], v[22:23], off offset:32
	v_pk_mul_f32 v[22:23], v[40:41], v[20:21] op_sel_hi:[1,0]
	v_pk_mul_f32 v[24:25], v[42:43], v[20:21] op_sel_hi:[1,0]
	ds_bpermute_b32 v21, v166, v0
	v_mfma_f32_16x16x32_bf16 v[2:5], v[208:211], v[196:199], v[2:5]
	v_cvt_pk_bf16_f32 v22, v22, v23
	v_cvt_pk_bf16_f32 v23, v24, v25
	global_store_dwordx2 v[30:31], v[22:23], off offset:64
	s_waitcnt lgkmcnt(0)
	v_add_f32_e32 v0, v0, v21
	v_pk_mul_f32 v[6:7], v[6:7], v[20:21] op_sel_hi:[1,0]
	v_pk_mul_f32 v[8:9], v[8:9], v[20:21] op_sel_hi:[1,0]
	v_div_scale_f32 v20, s[4:5], v0, v0, 1.0
	v_rcp_f32_e32 v21, v20
	v_cvt_pk_bf16_f32 v6, v6, v7
	v_cvt_pk_bf16_f32 v7, v8, v9
	global_store_dwordx2 v[30:31], v[6:7], off offset:96
	v_fma_f32 v6, -v20, v21, 1.0
	v_fmac_f32_e32 v21, v6, v21
	v_div_scale_f32 v6, vcc, 1.0, v0, 1.0
	v_mul_f32_e32 v7, v6, v21
	v_fma_f32 v8, -v20, v7, v6
	v_fmac_f32_e32 v7, v8, v21
	v_fma_f32 v6, -v20, v7, v6
	v_div_fmas_f32 v6, v6, v21, v7
	s_mov_b64 s[4:5], 0xa01e000
	v_div_fixup_f32 v0, v6, v0, 1.0
	v_lshl_add_u64 v[6:7], v[10:11], 0, s[4:5]
	s_mov_b32 s4, 0xa01e000
	v_pk_mul_f32 v[8:9], v[26:27], v[0:1] op_sel_hi:[1,0]
	v_pk_mul_f32 v[20:21], v[28:29], v[0:1] op_sel_hi:[1,0]
	v_add_co_u32_e32 v10, vcc, s4, v10
	v_cvt_pk_bf16_f32 v8, v8, v9
	v_cvt_pk_bf16_f32 v9, v20, v21
	v_addc_co_u32_e32 v11, vcc, 0, v11, vcc
	global_store_dwordx2 v[10:11], v[8:9], off
	v_pk_mul_f32 v[8:9], v[16:17], v[0:1] op_sel_hi:[1,0]
	v_pk_mul_f32 v[10:11], v[18:19], v[0:1] op_sel_hi:[1,0]
	v_cvt_pk_bf16_f32 v8, v8, v9
	v_cvt_pk_bf16_f32 v9, v10, v11
	global_store_dwordx2 v[6:7], v[8:9], off offset:32
	v_pk_mul_f32 v[8:9], v[12:13], v[0:1] op_sel_hi:[1,0]
	v_pk_mul_f32 v[10:11], v[14:15], v[0:1] op_sel_hi:[1,0]
	v_pk_mul_f32 v[2:3], v[2:3], v[0:1] op_sel_hi:[1,0]
	v_pk_mul_f32 v[4:5], v[4:5], v[0:1] op_sel_hi:[1,0]
	v_cvt_pk_bf16_f32 v8, v8, v9
	v_cvt_pk_bf16_f32 v9, v10, v11
	v_cvt_pk_bf16_f32 v2, v2, v3
	v_cvt_pk_bf16_f32 v3, v4, v5
	global_store_dwordx2 v[6:7], v[8:9], off offset:64
	global_store_dwordx2 v[6:7], v[2:3], off offset:96

.LBB0_1969:
	s_andn2_saveexec_b64 s[0:1], s[50:51]
	s_cbranch_execz .LBB0_1977
	v_subrev_u32_e32 v0, 36, v2
	s_movk_i32 s2, 0x1ff
	v_cmp_lt_u32_e32 vcc, s2, v0
	s_and_saveexec_b64 s[2:3], vcc
	s_xor_b64 s[2:3], exec, s[2:3]
	v_add_u32_e32 v2, 0xfffffddc, v2
	v_lshrrev_b32_e32 v2, 6, v2
	v_add_u32_e32 v3, 4, v2
	s_or_saveexec_b64 s[2:3], s[2:3]
	v_mov_b32_e32 v27, 0x800
	v_mov_b32_e32 v2, 15
	v_mov_b32_e32 v4, 4
	s_xor_b64 exec, exec, s[2:3]
	v_lshrrev_b32_e32 v3, 7, v0
	v_mov_b32_e32 v27, 0x1000
	v_mov_b32_e32 v2, 31
	v_mov_b32_e32 v4, 5
	s_or_b64 exec, exec, s[2:3]
	v_bfe_u32 v8, v0, v4, 2
	v_lshlrev_b32_e32 v4, 12, v3
	v_lshl_add_u32 v5, v3, 11, v161
	v_cmp_gt_u32_e32 vcc, 4, v3
	v_mul_u32_u24_e32 v3, 0x60, v8
	v_lshlrev_b32_e32 v119, 6, v8
	v_cndmask_b32_e32 v4, v5, v4, vcc
	v_mov_b32_e32 v5, v1
	v_lshlrev_b32_e32 v62, 1, v3
	v_lshlrev_b64 v[64:65], 9, v[4:5]
	v_mul_u32_u24_e32 v3, v119, v27
	v_mbcnt_lo_u32_b32 v5, -1, 0
	v_mbcnt_hi_u32_b32 v5, -1, v5
	v_lshlrev_b32_e32 v66, 1, v3
	v_or_b32_e32 v78, s10, v5
	v_mov_b64_e32 v[6:7], s[26:27]
	v_mul_hi_i32 v3, v78, s20
	v_lshrrev_b32_e32 v5, 31, v3
	v_ashrrev_i32_e32 v3, 1, v3
	v_add_u32_e32 v79, v3, v5
	v_mul_lo_u32 v3, v79, 12
	v_sub_u32_e32 v26, v78, v3
	v_add_u32_e32 v3, 0x100, v78
	v_mul_hi_i32 v5, v3, s20
	v_lshrrev_b32_e32 v8, 31, v5
	v_ashrrev_i32_e32 v5, 1, v5
	v_add_u32_e32 v80, v5, v8
	v_mul_lo_u32 v5, v80, 12
	v_sub_u32_e32 v52, v3, v5
	v_add_u32_e32 v3, 0x200, v78
	v_mov_b32_e32 v63, v1
	v_mad_u64_u32 v[6:7], s[2:3], v4, s18, v[6:7]
	v_lshlrev_b32_e32 v110, 3, v26
	v_mul_hi_i32 v5, v3, s20
	v_lshl_add_u64 v[48:49], v[6:7], 0, v[62:63]
	v_lshlrev_b32_e32 v112, 3, v52
	v_lshrrev_b32_e32 v8, 31, v5
	v_ashrrev_i32_e32 v5, 1, v5
	v_ashrrev_i32_e32 v111, 31, v110
	v_add_u32_e32 v81, v5, v8
	v_mad_i64_i32 v[8:9], s[2:3], v79, s18, v[48:49]
	v_lshlrev_b64 v[68:69], 1, v[110:111]
	v_ashrrev_i32_e32 v113, 31, v112
	v_lshl_add_u64 v[8:9], v[8:9], 0, v[68:69]
	v_mad_i64_i32 v[10:11], s[2:3], v80, s18, v[48:49]
	v_lshlrev_b64 v[70:71], 1, v[112:113]
	v_mul_lo_u32 v5, v81, 12
	v_lshl_add_u64 v[10:11], v[10:11], 0, v[70:71]
	global_load_dwordx4 v[28:31], v[8:9], off
	global_load_dwordx4 v[32:35], v[10:11], off
	v_sub_u32_e32 v53, v3, v5
	v_lshlrev_b32_e32 v114, 3, v53
	v_lshl_add_u64 v[6:7], s[28:29], 0, v[64:65]
	v_mov_b32_e32 v67, v1
	v_ashrrev_i32_e32 v82, 3, v78
	v_lshlrev_b32_e32 v3, 3, v78
	v_ashrrev_i32_e32 v115, 31, v114
	v_lshl_add_u64 v[6:7], v[6:7], 0, v[66:67]
	v_and_b32_e32 v3, 56, v3
	v_mad_i64_i32 v[8:9], s[2:3], v81, s18, v[48:49]
	v_lshlrev_b64 v[72:73], 1, v[114:115]
	v_mad_i64_i32 v[10:11], s[2:3], v82, v27, 0
	v_add_u32_e32 v83, 32, v82
	v_lshl_add_u64 v[8:9], v[8:9], 0, v[72:73]
	v_lshl_add_u64 v[10:11], v[10:11], 1, v[6:7]
	v_lshlrev_b32_e32 v124, 1, v3
	v_mov_b32_e32 v125, v1
	v_lshl_add_u64 v[50:51], v[10:11], 0, v[124:125]
	global_load_dwordx4 v[36:39], v[8:9], off
	global_load_dwordx4 v[40:43], v[50:51], off
	v_mad_i64_i32 v[8:9], s[2:3], v83, v27, 0
	v_lshl_add_u64 v[6:7], v[8:9], 1, v[6:7]
	v_lshl_add_u64 v[58:59], v[6:7], 0, v[124:125]
	global_load_dwordx4 v[44:47], v[58:59], off
	v_and_b32_e32 v0, v2, v0
	v_lshl_add_u32 v0, v0, 7, v4
	v_mov_b64_e32 v[2:3], s[12:13]
	v_ashrrev_i32_e32 v5, 1, v78
	v_mad_u64_u32 v[2:3], s[2:3], v0, s18, v[2:3]
	v_mad_u64_u32 v[74:75], s[2:3], v4, s18, 0
	v_and_b32_e32 v84, 15, v78
	v_bfe_u32 v4, v78, 4, 2
	v_and_b32_e32 v121, 0xffffffe0, v5
	v_lshl_add_u64 v[2:3], v[2:3], 0, v[62:63]
	v_or_b32_e32 v120, v121, v84
	v_lshlrev_b32_e32 v76, 4, v4
	v_mov_b32_e32 v77, v1
	v_mul_lo_u32 v54, v79, s68
	v_lshl_add_u64 v[2:3], v[2:3], 0, v[76:77]
	v_or_b32_e32 v6, 16, v120
	v_lshlrev_b32_e32 v143, 1, v54
	v_lshlrev_b32_e32 v26, 4, v26
	v_lshlrev_b32_e32 v118, 3, v4
	v_mad_i64_i32 v[4:5], s[2:3], v120, s18, v[2:3]
	v_mad_i64_i32 v[2:3], s[2:3], v6, s18, v[2:3]
	v_add3_u32 v26, s92, v143, v26
	global_load_dwordx4 v[22:25], v[4:5], off
	global_load_dwordx4 v[14:17], v[4:5], off offset:64
	global_load_dwordx4 v[6:9], v[4:5], off offset:128
	global_load_dwordx4 v[18:21], v[2:3], off
	global_load_dwordx4 v[10:13], v[2:3], off offset:64
	s_nop 0
	global_load_dwordx4 v[2:5], v[2:3], off offset:128
	s_waitcnt lgkmcnt(0)
	s_barrier
	v_lshrrev_b32_e32 v77, 6, v27
	v_mov_b32_e32 v126, 0
	s_mov_b32 s4, 0
	v_add_u32_e32 v151, -2, v77
	v_mov_b32_e32 v153, 0xf149f2ca
	v_mov_b32_e32 v113, 0xf149f2ca
	v_mov_b32_e32 v127, v126
	s_waitcnt vmcnt(0)
	ds_write_b128 v26, v[28:31]
	v_mul_lo_u32 v26, v80, s68
	v_lshlrev_b32_e32 v145, 1, v26
	v_lshlrev_b32_e32 v26, 4, v52
	v_add3_u32 v26, s92, v145, v26
	ds_write_b128 v26, v[32:35]
	v_mul_lo_u32 v26, v81, s68
	v_lshlrev_b32_e32 v147, 1, v26
	v_lshlrev_b32_e32 v26, 4, v53
	v_add3_u32 v26, s92, v147, v26
	v_lshl_add_u64 v[28:29], v[48:49], 0, s[38:39]
	v_mad_i64_i32 v[30:31], s[2:3], v79, s18, v[28:29]
	v_mad_i64_i32 v[32:33], s[2:3], v80, s18, v[28:29]
	v_mad_i64_i32 v[28:29], s[2:3], v81, s18, v[28:29]
	v_lshl_add_u64 v[30:31], v[30:31], 0, v[68:69]
	v_lshl_add_u64 v[28:29], v[28:29], 0, v[72:73]
	v_lshl_add_u64 v[32:33], v[32:33], 0, v[70:71]
	ds_write_b128 v26, v[36:39]
	v_mul_lo_u32 v26, v82, s52
	v_lshlrev_b32_e32 v149, 1, v26
	v_add3_u32 v26, s92, v149, v124
	ds_write_b128 v26, v[40:43] offset:13312
	ds_write_b128 v26, v[44:47] offset:17920
	global_load_dwordx4 v[54:57], v[30:31], off
	global_load_dwordx4 v[46:49], v[32:33], off
	global_load_dwordx4 v[42:45], v[28:29], off
	s_nop 0
	global_load_dwordx4 v[50:53], v[50:51], off offset:128
	s_nop 0
	global_load_dwordx4 v[58:61], v[58:59], off offset:128
	v_mul_u32_u24_e32 v28, 0x68, v84
	v_lshlrev_b32_e32 v111, 1, v28
	v_lshlrev_b32_e32 v28, 6, v84
	v_or_b32_e32 v29, 0x400, v28
	v_sub_u32_e32 v125, 0, v28
	v_sub_u32_e32 v137, 0, v29
	v_or_b32_e32 v29, 0x800, v28
	v_or_b32_e32 v28, 0xc00, v28
	v_sub_u32_e32 v141, 0, v28
	v_lshlrev_b32_e32 v28, 1, v83
	v_and_b32_e32 v30, 7, v78
	v_sub_u32_e32 v139, 0, v29
	v_mad_i64_i32 v[28:29], s[2:3], v28, v27, v[64:65]
	v_lshlrev_b32_e32 v30, 4, v30
	v_mov_b32_e32 v31, v1
	v_lshl_add_u64 v[28:29], v[28:29], 0, v[30:31]
	v_lshl_add_u64 v[28:29], v[28:29], 0, v[66:67]
	v_lshl_add_u64 v[116:117], v[28:29], 0, s[40:41]
	v_lshlrev_b32_e32 v28, 1, v82
	v_mad_i64_i32 v[28:29], s[2:3], v28, v27, v[64:65]
	v_lshl_add_u64 v[28:29], v[28:29], 0, v[30:31]
	v_lshl_add_u64 v[28:29], v[28:29], 0, v[66:67]
	v_lshl_add_u64 v[128:129], v[28:29], 0, s[40:41]
	v_mad_i64_i32 v[28:29], s[2:3], v81, s18, v[74:75]
	v_lshl_add_u64 v[28:29], v[28:29], 0, v[72:73]
	v_lshl_add_u64 v[28:29], v[28:29], 0, v[62:63]
	v_lshl_add_u64 v[130:131], v[28:29], 0, s[42:43]
	v_mad_i64_i32 v[28:29], s[2:3], v80, s18, v[74:75]
	v_lshl_add_u64 v[28:29], v[28:29], 0, v[70:71]
	v_lshl_add_u64 v[28:29], v[28:29], 0, v[62:63]
	v_lshl_add_u64 v[132:133], v[28:29], 0, s[42:43]
	v_mad_i64_i32 v[28:29], s[2:3], v79, s18, v[74:75]
	v_lshl_add_u64 v[28:29], v[28:29], 0, v[68:69]
	v_mov_b32_e32 v26, v1
	v_lshl_add_u64 v[28:29], v[28:29], 0, v[62:63]
	s_waitcnt lgkmcnt(0)
	s_barrier
	v_add3_u32 v123, s92, v76, v111
	v_lshl_add_u64 v[134:135], v[28:29], 0, s[42:43]
	s_mov_b64 s[2:3], 0
	v_mov_b32_e32 v27, v26
	v_mov_b32_e32 v28, v26
	v_mov_b32_e32 v29, v26
	v_mov_b32_e32 v30, v26
	v_mov_b32_e32 v31, v26
	v_mov_b32_e32 v32, v26
	v_mov_b32_e32 v33, v26
	v_mov_b32_e32 v34, v26
	v_mov_b32_e32 v35, v26
	v_mov_b32_e32 v36, v26
	v_mov_b32_e32 v37, v26
	v_mov_b32_e32 v38, v26
	v_mov_b32_e32 v39, v26
	v_mov_b32_e32 v40, v26
	v_mov_b32_e32 v41, v26
	v_mov_b32_e32 v62, v26
	v_mov_b32_e32 v63, v26
	v_mov_b32_e32 v64, v26
	v_mov_b32_e32 v65, v26
	v_mov_b32_e32 v66, v26
	v_mov_b32_e32 v67, v26
	v_mov_b32_e32 v68, v26
	v_mov_b32_e32 v69, v26
	v_mov_b32_e32 v70, v26
	v_mov_b32_e32 v71, v26
	v_mov_b32_e32 v72, v26
	v_mov_b32_e32 v73, v26
	v_mov_b32_e32 v74, v26
	v_mov_b32_e32 v75, v26
	v_mov_b32_e32 v76, v26
	v_mov_b32_e32 v77, v26
	v_readlane_b32 s98, v236, 62
	s_nop 3
	s_cmp_lt_u32 s98, 4
	s_cbranch_scc1 .Lprio_skip_1
	s_setprio 1
.Lprio_skip_1:
.LBB0_1975:
	s_and_b32 s5, s4, 1
	s_mul_i32 s8, s5, 0x5800
	v_mov_b32_e32 v78, 0
	v_add_u32_e32 v138, s8, v123
	ds_read_b128 v[82:85], v138
	ds_read_b128 v[86:89], v138 offset:3328
	ds_read_b128 v[90:93], v138 offset:6656
	ds_read_b128 v[94:97], v138 offset:9984
	v_mov_b32_e32 v79, v78
	v_mov_b32_e32 v80, v78
	v_mov_b32_e32 v81, v78
	v_mov_b32_e32 v136, v153
	v_mov_b32_e32 v115, v113
	s_waitcnt lgkmcnt(0)
	v_mfma_f32_16x16x32_bf16 v[98:101], v[82:85], v[22:25], v[78:81]
	v_and_b32_e32 v148, 64, v170
	v_xor_b32_e32 v146, 16, v170
	v_add_u32_e32 v148, 64, v148
	v_mfma_f32_16x16x32_bf16 v[102:105], v[86:89], v[22:25], v[78:81]
	v_cmp_lt_i32_e32 vcc, v146, v148
	v_add_u32_e32 v140, 0xd00, v138
	v_add_u32_e32 v142, 0x1a00, v138
	v_mfma_f32_16x16x32_bf16 v[106:109], v[90:93], v[22:25], v[78:81]
	v_cndmask_b32_e32 v146, v170, v146, vcc
	v_lshlrev_b32_e32 v165, 2, v146
	v_add_u32_e32 v144, 0x2700, v138
	v_mfma_f32_16x16x32_bf16 v[152:155], v[94:97], v[22:25], v[78:81]
	s_xor_b32 s5, s5, 1
	s_mulk_i32 s5, 0x5800
	s_add_i32 s5, s92, s5
	v_mfma_f32_16x16x32_bf16 v[82:85], v[82:85], v[18:21], v[78:81]
	s_add_i32 s4, s4, 1
	v_mfma_f32_16x16x32_bf16 v[86:89], v[86:89], v[18:21], v[78:81]
	v_mfma_f32_16x16x32_bf16 v[90:93], v[90:93], v[18:21], v[78:81]
	v_mfma_f32_16x16x32_bf16 v[78:81], v[94:97], v[18:21], v[78:81]
	ds_read_b128 v[94:97], v138 offset:64
	ds_read_b128 v[166:169], v138 offset:3392
	ds_read_b128 v[172:175], v138 offset:6720
	ds_read_b128 v[176:179], v138 offset:10048
	s_waitcnt lgkmcnt(0)
	v_mfma_f32_16x16x32_bf16 v[98:101], v[94:97], v[14:17], v[98:101]
	v_mfma_f32_16x16x32_bf16 v[102:105], v[166:169], v[14:17], v[102:105]
	v_mfma_f32_16x16x32_bf16 v[180:183], v[172:175], v[14:17], v[106:109]
	v_mfma_f32_16x16x32_bf16 v[152:155], v[176:179], v[14:17], v[152:155]
	v_mfma_f32_16x16x32_bf16 v[86:89], v[166:169], v[10:13], v[86:89]
	v_mfma_f32_16x16x32_bf16 v[166:169], v[172:175], v[10:13], v[90:93]
	v_mfma_f32_16x16x32_bf16 v[78:81], v[176:179], v[10:13], v[78:81]
	s_nop 1
	ds_read_b128 v[90:93], v138 offset:128
	ds_read_b128 v[172:175], v138 offset:3456
	ds_read_b128 v[176:179], v138 offset:6784
	ds_read_b128 v[184:187], v138 offset:10112
	s_waitcnt lgkmcnt(0)
	v_mfma_f32_16x16x32_bf16 v[106:109], v[90:93], v[6:9], v[98:101]
	v_mfma_f32_16x16x32_bf16 v[102:105], v[172:175], v[6:9], v[102:105]
	v_mfma_f32_16x16x32_bf16 v[98:101], v[176:179], v[6:9], v[180:183]
	s_nop 5
	v_max3_f32 v113, v106, s70, v107
	v_max3_f32 v113, v113, v108, v109
	v_max3_f32 v113, v113, v102, v103
	v_mfma_f32_16x16x32_bf16 v[82:85], v[94:97], v[10:13], v[82:85]
	v_max3_f32 v113, v113, v104, v105
	v_max3_f32 v113, v113, v98, v99
	v_max3_f32 v113, v113, v100, v101
	v_mfma_f32_16x16x32_bf16 v[94:97], v[184:187], v[6:9], v[152:155]
	v_mfma_f32_16x16x32_bf16 v[90:93], v[90:93], v[2:5], v[82:85]
	v_mfma_f32_16x16x32_bf16 v[82:85], v[176:179], v[2:5], v[166:169]
	s_nop 5
	v_max3_f32 v113, v113, v94, v95
	v_max3_f32 v113, v113, v96, v97
	ds_bpermute_b32 v146, v165, v113
	v_mfma_f32_16x16x32_bf16 v[86:89], v[172:175], v[2:5], v[86:89]
	v_lshlrev_b32_e32 v167, 1, v112
	s_waitcnt lgkmcnt(0)
	v_max_f32_e32 v146, v146, v146
	v_max_f32_e32 v113, v113, v146
	v_xor_b32_e32 v146, 32, v170
	v_cmp_lt_i32_e32 vcc, v146, v148
	v_mfma_f32_16x16x32_bf16 v[78:81], v[184:187], v[2:5], v[78:81]
	s_nop 0
	v_cndmask_b32_e32 v146, v170, v146, vcc
	v_lshlrev_b32_e32 v166, 2, v146
	ds_bpermute_b32 v146, v166, v113
	v_cmp_eq_u32_e32 vcc, s4, v151
	s_or_b64 s[2:3], vcc, s[2:3]
	s_waitcnt lgkmcnt(0)
	v_max3_f32 v113, v115, v113, v146
	v_sub_f32_e32 v94, v94, v113
	v_exp_f32_e32 v200, v94
	v_sub_f32_e32 v94, v95, v113
	v_exp_f32_e32 v202, v94
	v_sub_f32_e32 v94, v96, v113
	v_exp_f32_e32 v204, v94
	v_sub_f32_e32 v94, v97, v113
	v_exp_f32_e32 v206, v94
	v_max3_f32 v94, v90, s70, v91
	v_max3_f32 v94, v94, v92, v93
	v_max3_f32 v94, v94, v86, v87
	v_max3_f32 v94, v94, v88, v89
	v_max3_f32 v94, v94, v82, v83
	v_max3_f32 v94, v94, v84, v85
	v_max3_f32 v94, v94, v78, v79
	v_max3_f32 v94, v94, v80, v81
	ds_bpermute_b32 v95, v165, v94
	v_sub_f32_e32 v102, v102, v113
	v_sub_f32_e32 v98, v98, v113
	v_exp_f32_e32 v184, v102
	v_sub_f32_e32 v102, v103, v113
	s_waitcnt lgkmcnt(0)
	v_max_f32_e32 v95, v95, v95
	v_max_f32_e32 v94, v94, v95
	ds_bpermute_b32 v95, v166, v94
	v_exp_f32_e32 v192, v98
	v_sub_f32_e32 v98, v99, v113
	v_exp_f32_e32 v186, v102
	v_sub_f32_e32 v102, v104, v113
	s_waitcnt lgkmcnt(0)
	v_max3_f32 v153, v136, v94, v95
	v_sub_f32_e32 v86, v86, v153
	v_sub_f32_e32 v82, v82, v153
	v_sub_f32_e32 v78, v78, v153
	v_exp_f32_e32 v194, v98
	v_sub_f32_e32 v98, v100, v113
	v_exp_f32_e32 v185, v86
	v_sub_f32_e32 v86, v87, v153
	v_exp_f32_e32 v193, v82
	v_sub_f32_e32 v82, v83, v153
	v_exp_f32_e32 v201, v78
	v_sub_f32_e32 v78, v79, v153
	v_exp_f32_e32 v188, v102
	v_sub_f32_e32 v102, v105, v113
	v_exp_f32_e32 v196, v98
	v_sub_f32_e32 v98, v101, v113
	v_sub_f32_e32 v94, v136, v153
	v_exp_f32_e32 v187, v86
	v_sub_f32_e32 v86, v88, v153
	v_exp_f32_e32 v195, v82
	v_sub_f32_e32 v82, v84, v153
	v_exp_f32_e32 v203, v78
	v_sub_f32_e32 v78, v80, v153
	v_exp_f32_e32 v190, v102
	v_exp_f32_e32 v198, v98
	v_exp_f32_e32 v189, v86
	v_sub_f32_e32 v86, v89, v153
	v_exp_f32_e32 v197, v82
	v_sub_f32_e32 v82, v85, v153
	v_exp_f32_e32 v205, v78
	v_sub_f32_e32 v78, v81, v153
	v_exp_f32_e32 v209, v94
	v_add_u32_e32 v94, v138, v125
	v_add_u32_e32 v98, v140, v137
	v_add_u32_e32 v102, v142, v139
	v_sub_f32_e32 v106, v106, v113
	v_exp_f32_e32 v191, v86
	v_exp_f32_e32 v199, v82
	v_exp_f32_e32 v207, v78
	ds_read_b128 v[78:81], v94 offset:13312
	ds_read_b128 v[82:85], v98 offset:13312
	ds_read_b128 v[86:89], v102 offset:13312
	v_exp_f32_e32 v154, v106
	v_sub_f32_e32 v106, v107, v113
	v_sub_f32_e32 v90, v90, v153
	v_exp_f32_e32 v168, v106
	v_sub_f32_e32 v106, v108, v113
	v_exp_f32_e32 v155, v90
	v_sub_f32_e32 v90, v91, v153
	v_sub_f32_e32 v115, v115, v113
	v_exp_f32_e32 v180, v106
	v_sub_f32_e32 v106, v109, v113
	v_exp_f32_e32 v169, v90
	v_exp_f32_e32 v182, v106
	v_exp_f32_e32 v208, v115
	v_sub_f32_e32 v90, v92, v153
	v_exp_f32_e32 v181, v90
	v_sub_f32_e32 v90, v93, v153
	v_exp_f32_e32 v183, v90
	v_add_u32_e32 v106, v144, v141
	v_cvt_pk_bf16_f32 v172, v154, v168
	v_cvt_pk_bf16_f32 v176, v155, v169
	v_pk_add_f32 v[154:155], v[154:155], 0 op_sel_hi:[1,0]
	ds_read_b128 v[90:93], v106 offset:13312
	ds_read_b128 v[94:97], v94 offset:13376
	ds_read_b128 v[98:101], v98 offset:13376
	ds_read_b128 v[102:105], v102 offset:13376
	ds_read_b128 v[106:109], v106 offset:13376
	v_cvt_pk_bf16_f32 v173, v180, v182
	v_cvt_pk_bf16_f32 v174, v184, v186
	v_pk_add_f32 v[154:155], v[168:169], v[154:155]
	v_pk_mul_f32 v[76:77], v[76:77], v[208:209] op_sel_hi:[1,0]
	v_pk_mul_f32 v[74:75], v[74:75], v[208:209] op_sel_hi:[1,0]
	v_pk_mul_f32 v[72:73], v[72:73], v[208:209] op_sel_hi:[1,0]
	v_pk_mul_f32 v[70:71], v[70:71], v[208:209] op_sel_hi:[1,0]
	v_pk_mul_f32 v[68:69], v[68:69], v[208:209] op_sel_hi:[1,0]
	v_pk_mul_f32 v[66:67], v[66:67], v[208:209] op_sel_hi:[1,0]
	v_pk_mul_f32 v[64:65], v[64:65], v[208:209] op_sel_hi:[1,0]
	v_pk_mul_f32 v[62:63], v[62:63], v[208:209] op_sel_hi:[1,0]
	v_cvt_pk_bf16_f32 v175, v188, v190
	v_pk_add_f32 v[154:155], v[180:181], v[154:155]
	v_mov_b32_e32 v136, v209
	s_waitcnt lgkmcnt(0)
	v_mfma_f32_16x16x32_bf16 v[74:77], v[78:81], v[172:175], v[74:77]
	v_add_f32_e64 v154, v182, v154
	v_add_f32_e64 v155, v183, v155
	v_cvt_pk_bf16_f32 v177, v181, v183
	v_cvt_pk_bf16_f32 v178, v185, v187
	v_mfma_f32_16x16x32_bf16 v[70:73], v[82:85], v[172:175], v[70:73]
	v_add_f32_e64 v154, v184, v154
	v_add_f32_e64 v155, v185, v155
	v_pk_mul_f32 v[40:41], v[40:41], v[136:137] op_sel_hi:[1,0]
	v_pk_mul_f32 v[38:39], v[38:39], v[136:137] op_sel_hi:[1,0]
	v_mfma_f32_16x16x32_bf16 v[66:69], v[86:89], v[172:175], v[66:69]
	v_cvt_pk_bf16_f32 v179, v189, v191
	v_pk_add_f32 v[154:155], v[186:187], v[154:155]
	v_lshlrev_b32_e32 v168, 1, v114
	v_mfma_f32_16x16x32_bf16 v[62:65], v[90:93], v[172:175], v[62:65]
	v_mul_f32_e64 v36, v36, v136
	v_mul_f32_e64 v37, v37, v136
	v_pk_mul_f32 v[34:35], v[34:35], v[136:137] op_sel_hi:[1,0]
	v_pk_mul_f32 v[32:33], v[32:33], v[136:137] op_sel_hi:[1,0]
	v_mfma_f32_16x16x32_bf16 v[38:41], v[78:81], v[176:179], v[38:41]
	v_cvt_pk_bf16_f32 v78, v192, v194
	v_cvt_pk_bf16_f32 v79, v196, v198
	v_cvt_pk_bf16_f32 v80, v200, v202
	v_cvt_pk_bf16_f32 v81, v204, v206
	v_pk_mul_f32 v[30:31], v[30:31], v[136:137] op_sel_hi:[1,0]
	v_pk_mul_f32 v[28:29], v[28:29], v[136:137] op_sel_hi:[1,0]
	v_mfma_f32_16x16x32_bf16 v[74:77], v[94:97], v[78:81], v[74:77]
	v_mul_f32_e64 v26, v26, v136
	v_mul_f32_e64 v27, v27, v136
	v_mfma_f32_16x16x32_bf16 v[70:73], v[98:101], v[78:81], v[70:73]
	v_mfma_f32_16x16x32_bf16 v[66:69], v[102:105], v[78:81], v[66:69]
	v_mfma_f32_16x16x32_bf16 v[62:65], v[106:109], v[78:81], v[62:65]
	v_add_f32_e64 v78, v188, v154
	v_add_f32_e64 v79, v189, v155
	v_lshlrev_b32_e32 v155, 1, v110
	v_pk_add_f32 v[78:79], v[190:191], v[78:79]
	v_mfma_f32_16x16x32_bf16 v[34:37], v[82:85], v[176:179], v[34:37]
	v_add_f32_e64 v78, v192, v78
	v_add_f32_e64 v79, v193, v79
	v_cvt_pk_bf16_f32 v82, v193, v195
	v_pk_add_f32 v[78:79], v[194:195], v[78:79]
	v_mfma_f32_16x16x32_bf16 v[30:33], v[86:89], v[176:179], v[30:33]
	v_add_f32_e64 v78, v196, v78
	v_add_f32_e64 v79, v197, v79
	v_cvt_pk_bf16_f32 v83, v197, v199
	v_pk_add_f32 v[78:79], v[198:199], v[78:79]
	v_mfma_f32_16x16x32_bf16 v[26:29], v[90:93], v[176:179], v[26:29]
	v_add_f32_e64 v78, v200, v78
	v_add_f32_e64 v79, v201, v79
	v_cvt_pk_bf16_f32 v84, v201, v203
	v_pk_add_f32 v[78:79], v[202:203], v[78:79]
	v_cvt_pk_bf16_f32 v85, v205, v207
	v_pk_add_f32 v[78:79], v[204:205], v[78:79]
	s_nop 0
	v_pk_add_f32 v[78:79], v[206:207], v[78:79]
	v_mfma_f32_16x16x32_bf16 v[38:41], v[94:97], v[82:85], v[38:41]
	v_fma_f32 v126, v126, v208, v78
	v_fma_f32 v127, v127, v209, v79
	v_add3_u32 v78, s5, v143, v155
	s_waitcnt vmcnt(0)
	ds_write_b128 v78, v[54:57]
	v_add3_u32 v54, s5, v145, v167
	ds_write_b128 v54, v[46:49]
	v_add3_u32 v46, s5, v147, v168
	ds_write_b128 v46, v[42:45]
	v_add3_u32 v42, s5, v149, v124
	ds_write_b128 v42, v[50:53] offset:13312
	ds_write_b128 v42, v[58:61] offset:17920
	v_lshl_add_u64 v[42:43], s[12:13], 0, v[134:135]
	v_lshl_add_u64 v[50:51], s[12:13], 0, v[128:129]
	global_load_dwordx4 v[54:57], v[42:43], off
	v_lshl_add_u64 v[58:59], s[12:13], 0, v[116:117]
	global_load_dwordx4 v[50:53], v[50:51], off
	v_lshl_add_u64 v[42:43], s[12:13], 0, v[132:133]
	global_load_dwordx4 v[46:49], v[42:43], off
	v_mfma_f32_16x16x32_bf16 v[34:37], v[98:101], v[82:85], v[34:37]
	global_load_dwordx4 v[58:61], v[58:59], off
	v_lshl_add_u64 v[42:43], s[12:13], 0, v[130:131]
	global_load_dwordx4 v[42:45], v[42:43], off
	v_mfma_f32_16x16x32_bf16 v[30:33], v[102:105], v[82:85], v[30:33]
	v_lshl_add_u64 v[116:117], v[116:117], 0, s[44:45]
	v_lshl_add_u64 v[128:129], v[128:129], 0, s[44:45]
	v_lshl_add_u64 v[130:131], v[130:131], 0, s[38:39]
	v_mfma_f32_16x16x32_bf16 v[26:29], v[106:109], v[82:85], v[26:29]
	v_lshl_add_u64 v[132:133], v[132:133], 0, s[38:39]
	v_lshl_add_u64 v[134:135], v[134:135], 0, s[38:39]
	s_waitcnt lgkmcnt(0)
	s_barrier
	s_andn2_b64 exec, exec, s[2:3]
	s_cbranch_execnz .LBB0_1975
	s_setprio 0
	s_or_b64 exec, exec, s[2:3]
	v_and_b32_e32 v78, 1, v151
	v_mov_b32_e32 v169, s92
	v_mad_u32_u24 v79, v78, s69, v169
	v_lshlrev_b32_e32 v80, 1, v118
	v_mov_b32_e32 v78, v1
	v_add3_u32 v171, v79, v80, v111
	ds_read_b128 v[82:85], v171
	ds_read_b128 v[86:89], v171 offset:64
	ds_read_b128 v[94:97], v171 offset:3328
	ds_read_b128 v[98:101], v171 offset:128
	v_mov_b32_e32 v79, v78
	v_mov_b32_e32 v80, v78
	v_mov_b32_e32 v81, v78
	ds_read_b128 v[106:109], v171 offset:6656
	ds_read_b128 v[114:117], v171 offset:6720
	s_waitcnt lgkmcnt(0)
	v_mfma_f32_16x16x32_bf16 v[90:93], v[82:85], v[22:25], v[78:81]
	ds_read_b128 v[132:135], v171 offset:9984
	ds_read_b128 v[172:175], v171 offset:6784
	ds_read_b128 v[180:183], v171 offset:3392
	ds_read_b128 v[184:187], v171 offset:3456
	ds_read_b128 v[188:191], v171 offset:10048
	ds_read_b128 v[192:195], v171 offset:10112
	v_mfma_f32_16x16x32_bf16 v[102:105], v[94:97], v[22:25], v[78:81]
	v_add_u32_e32 v200, 0x2700, v171
	v_ashrrev_i32_e32 v121, 31, v121
	v_mfma_f32_16x16x32_bf16 v[128:131], v[106:109], v[22:25], v[78:81]
	v_mfma_f32_16x16x32_bf16 v[90:93], v[86:89], v[14:17], v[90:93]
	s_waitcnt lgkmcnt(0)
	v_mfma_f32_16x16x32_bf16 v[176:179], v[132:135], v[22:25], v[78:81]
	v_mfma_f32_16x16x32_bf16 v[102:105], v[180:183], v[14:17], v[102:105]
	v_mfma_f32_16x16x32_bf16 v[128:131], v[114:117], v[14:17], v[128:131]
	v_mfma_f32_16x16x32_bf16 v[90:93], v[98:101], v[6:9], v[90:93]
	v_mfma_f32_16x16x32_bf16 v[176:179], v[188:191], v[14:17], v[176:179]
	v_mfma_f32_16x16x32_bf16 v[102:105], v[184:187], v[6:9], v[102:105]
	s_nop 5
	v_max3_f32 v110, v90, s70, v91
	v_max3_f32 v110, v110, v92, v93
	v_mfma_f32_16x16x32_bf16 v[196:199], v[172:175], v[6:9], v[128:131]
	v_mfma_f32_16x16x32_bf16 v[176:179], v[192:195], v[6:9], v[176:179]
	v_max3_f32 v110, v110, v102, v103
	v_max3_f32 v110, v110, v104, v105
	s_nop 4
	v_max3_f32 v110, v110, v196, v197
	v_max3_f32 v110, v110, v198, v199
	v_mfma_f32_16x16x32_bf16 v[82:85], v[82:85], v[18:21], v[78:81]
	v_max3_f32 v110, v110, v176, v177
	v_max3_f32 v110, v110, v178, v179
	ds_bpermute_b32 v111, v165, v110
	v_mfma_f32_16x16x32_bf16 v[94:97], v[94:97], v[18:21], v[78:81]
	v_add_u32_e32 v129, 0xd00, v171
	v_add_u32_e32 v131, 0x1a00, v171
	s_waitcnt lgkmcnt(0)
	v_max_f32_e32 v111, v111, v111
	v_max_f32_e32 v110, v110, v111
	ds_bpermute_b32 v111, v166, v110
	v_mfma_f32_16x16x32_bf16 v[106:109], v[106:109], v[18:21], v[78:81]
	s_waitcnt lgkmcnt(0)
	v_max3_f32 v228, v113, v110, v111
	v_sub_f32_e32 v90, v90, v228
	v_exp_f32_e32 v229, v90
	v_sub_f32_e32 v90, v91, v228
	v_exp_f32_e32 v230, v90
	v_sub_f32_e32 v90, v92, v228
	v_exp_f32_e32 v148, v90
	v_sub_f32_e32 v90, v93, v228
	v_mfma_f32_16x16x32_bf16 v[78:81], v[132:135], v[18:21], v[78:81]
	v_exp_f32_e32 v130, v90
	v_sub_f32_e32 v90, v102, v228
	v_exp_f32_e32 v134, v90
	v_mfma_f32_16x16x32_bf16 v[82:85], v[86:89], v[10:13], v[82:85]
	v_sub_f32_e32 v86, v104, v228
	v_sub_f32_e32 v90, v103, v228
	v_exp_f32_e32 v128, v86
	v_mfma_f32_16x16x32_bf16 v[86:89], v[180:183], v[10:13], v[94:97]
	v_exp_f32_e32 v138, v90
	v_sub_f32_e32 v90, v105, v228
	v_exp_f32_e32 v132, v90
	v_mfma_f32_16x16x32_bf16 v[90:93], v[114:117], v[10:13], v[106:109]
	v_sub_f32_e32 v110, v113, v228
	v_exp_f32_e32 v216, v110
	v_sub_f32_e32 v94, v196, v228
	v_mfma_f32_16x16x32_bf16 v[78:81], v[188:191], v[10:13], v[78:81]
	v_exp_f32_e32 v136, v94
	v_sub_f32_e32 v94, v197, v228
	v_exp_f32_e32 v140, v94
	v_mfma_f32_16x16x32_bf16 v[180:183], v[98:101], v[2:5], v[82:85]
	v_sub_f32_e32 v94, v198, v228
	v_exp_f32_e32 v142, v94
	v_sub_f32_e32 v94, v199, v228
	v_mfma_f32_16x16x32_bf16 v[184:187], v[184:187], v[2:5], v[86:89]
	v_sub_f32_e32 v82, v176, v228
	v_exp_f32_e32 v146, v82
	v_sub_f32_e32 v82, v177, v228
	v_mfma_f32_16x16x32_bf16 v[114:117], v[172:175], v[2:5], v[90:93]
	v_exp_f32_e32 v150, v82
	v_sub_f32_e32 v82, v178, v228
	v_exp_f32_e32 v152, v82
	v_mfma_f32_16x16x32_bf16 v[110:113], v[192:195], v[2:5], v[78:81]
	v_sub_f32_e32 v82, v179, v228
	v_exp_f32_e32 v144, v94
	v_exp_f32_e32 v154, v82
	v_max3_f32 v78, v180, s70, v181
	v_max3_f32 v78, v78, v182, v183
	v_max3_f32 v78, v78, v184, v185
	v_max3_f32 v78, v78, v186, v187
	v_add_u32_e32 v79, v129, v137
	v_bitop3_b32 v129, v151, 1, v151 bitop3:0xc
	v_max3_f32 v78, v78, v114, v115
	v_mad_u32_u24 v129, v129, s69, v169
	v_max3_f32 v133, v78, v116, v117
	v_add_u32_e32 v78, v171, v125
	v_add_u32_e32 v80, v131, v139
	v_add_u32_e32 v81, v200, v141
	v_add3_u32 v131, v129, v143, v155
	ds_read_b128 v[106:109], v78 offset:13312
	ds_read_b128 v[90:93], v78 offset:13376
	ds_read_b128 v[102:105], v79 offset:13312
	ds_read_b128 v[86:89], v79 offset:13376
	ds_read_b128 v[98:101], v80 offset:13312
	ds_read_b128 v[82:85], v80 offset:13376
	ds_read_b128 v[94:97], v81 offset:13312
	ds_read_b128 v[78:81], v81 offset:13376
	s_waitcnt vmcnt(0)
	ds_write_b128 v131, v[54:57]
	v_add3_u32 v54, v129, v145, v167
	ds_write_b128 v54, v[46:49]
	v_add3_u32 v46, v129, v147, v168
	ds_write_b128 v46, v[42:45]
	v_add3_u32 v42, v129, v149, v124
	ds_write_b128 v42, v[50:53] offset:13312
	ds_write_b128 v42, v[58:61] offset:17920
	v_max3_f32 v42, v133, v110, v111
	v_max3_f32 v42, v42, v112, v113
	ds_bpermute_b32 v43, v165, v42
	v_mov_b32_e32 v46, v1
	s_waitcnt lgkmcnt(0)
	s_barrier
	ds_read_b128 v[50:53], v123 offset:22528
	ds_read_b128 v[54:57], v123 offset:25856
	v_max_f32_e32 v43, v43, v43
	v_pk_mul_f32 v[44:45], v[68:69], v[216:217] op_sel_hi:[1,0]
	v_max_f32_e32 v68, v42, v43
	ds_bpermute_b32 v69, v166, v68
	ds_read_b128 v[58:61], v123 offset:29184
	ds_read_b128 v[172:175], v123 offset:22592
	ds_read_b128 v[188:191], v123 offset:32512
	ds_read_b128 v[192:195], v123 offset:22656
	ds_read_b128 v[200:203], v123 offset:29248
	ds_read_b128 v[224:227], v123 offset:25920
	v_mov_b32_e32 v47, v46
	v_mov_b32_e32 v48, v46
	v_mov_b32_e32 v49, v46
	v_mul_f32_e32 v126, v126, v216
	v_pk_mul_f32 v[76:77], v[76:77], v[216:217] op_sel_hi:[1,0]
	s_waitcnt lgkmcnt(8)
	v_mfma_f32_16x16x32_bf16 v[176:179], v[50:53], v[22:25], v[46:49]
	v_mul_f32_e64 v74, v74, v216
	v_mul_f32_e64 v75, v75, v216
	v_pk_mul_f32 v[72:73], v[72:73], v[216:217] op_sel_hi:[1,0]
	v_pk_mul_f32 v[70:71], v[70:71], v[216:217] op_sel_hi:[1,0]
	s_waitcnt lgkmcnt(7)
	v_mfma_f32_16x16x32_bf16 v[196:199], v[54:57], v[22:25], v[46:49]
	v_mul_f32_e64 v42, v66, v216
	v_mul_f32_e64 v43, v67, v216
	ds_read_b128 v[208:211], v123 offset:29312
	s_waitcnt lgkmcnt(6)
	v_mfma_f32_16x16x32_bf16 v[204:207], v[58:61], v[22:25], v[46:49]
	s_waitcnt lgkmcnt(4)
	v_mfma_f32_16x16x32_bf16 v[212:215], v[188:191], v[22:25], v[46:49]
	v_mul_f32_e64 v24, v64, v216
	v_mul_f32_e64 v25, v65, v216
	v_pk_mul_f32 v[22:23], v[62:63], v[216:217] op_sel_hi:[1,0]
	v_mfma_f32_16x16x32_bf16 v[62:65], v[50:53], v[18:21], v[46:49]
	v_max3_f32 v51, v153, v68, v69
	v_sub_f32_e32 v50, v180, v51
	v_sub_f32_e32 v52, v185, v51
	v_mfma_f32_16x16x32_bf16 v[216:219], v[54:57], v[18:21], v[46:49]
	v_exp_f32_e32 v55, v50
	v_sub_f32_e32 v50, v181, v51
	v_exp_f32_e32 v57, v50
	v_mfma_f32_16x16x32_bf16 v[220:223], v[58:61], v[18:21], v[46:49]
	v_sub_f32_e32 v50, v182, v51
	v_exp_f32_e32 v66, v52
	v_sub_f32_e32 v52, v186, v51
	v_mfma_f32_16x16x32_bf16 v[18:21], v[188:191], v[18:21], v[46:49]
	v_exp_f32_e32 v68, v52
	v_sub_f32_e32 v52, v187, v51
	v_sub_f32_e32 v53, v153, v51
	v_sub_f32_e32 v46, v183, v51
	v_exp_f32_e32 v54, v46
	v_sub_f32_e32 v46, v184, v51
	v_exp_f32_e32 v58, v46
	ds_read_b128 v[46:49], v123 offset:32576
	ds_read_b128 v[180:183], v123 offset:25984
	v_mfma_f32_16x16x32_bf16 v[176:179], v[172:175], v[14:17], v[176:179]
	ds_read_b128 v[184:187], v123 offset:32640
	v_exp_f32_e32 v50, v50
	v_exp_f32_e32 v52, v52
	s_waitcnt lgkmcnt(4)
	v_mfma_f32_16x16x32_bf16 v[188:191], v[224:227], v[14:17], v[196:199]
	v_mfma_f32_16x16x32_bf16 v[196:199], v[200:203], v[14:17], v[204:207]
	s_waitcnt lgkmcnt(2)
	v_mfma_f32_16x16x32_bf16 v[204:207], v[46:49], v[14:17], v[212:215]
	v_sub_f32_e32 v14, v114, v51
	v_exp_f32_e32 v56, v14
	v_sub_f32_e32 v14, v115, v51
	v_exp_f32_e32 v60, v14
	v_sub_f32_e32 v14, v116, v51
	v_mfma_f32_16x16x32_bf16 v[176:179], v[192:195], v[6:9], v[176:179]
	v_mfma_f32_16x16x32_bf16 v[172:175], v[172:175], v[10:13], v[62:65]
	s_nop 2
	v_exp_f32_e32 v62, v14
	v_sub_f32_e32 v14, v117, v51
	v_exp_f32_e32 v64, v14
	v_sub_f32_e32 v14, v110, v51
	s_waitcnt lgkmcnt(1)
	v_mfma_f32_16x16x32_bf16 v[188:191], v[180:183], v[6:9], v[188:191]
	v_exp_f32_e32 v110, v14
	v_sub_f32_e32 v14, v111, v51
	v_exp_f32_e32 v114, v14
	v_mfma_f32_16x16x32_bf16 v[212:215], v[224:227], v[10:13], v[216:219]
	v_mfma_f32_16x16x32_bf16 v[200:203], v[200:203], v[10:13], v[220:223]
	v_mfma_f32_16x16x32_bf16 v[16:19], v[46:49], v[10:13], v[18:21]
	v_sub_f32_e32 v10, v112, v51
	v_exp_f32_e32 v48, v10
	v_sub_f32_e32 v10, v113, v51
	v_mfma_f32_16x16x32_bf16 v[12:15], v[208:211], v[6:9], v[196:199]
	v_max3_f32 v21, v176, s70, v177
	v_max3_f32 v21, v21, v178, v179
	v_exp_f32_e32 v20, v10
	s_waitcnt lgkmcnt(0)
	v_mfma_f32_16x16x32_bf16 v[8:11], v[184:187], v[6:9], v[204:207]
	v_max3_f32 v21, v21, v188, v189
	v_max3_f32 v21, v21, v190, v191
	v_exp_f32_e32 v112, v53
	v_max3_f32 v21, v21, v12, v13
	v_max3_f32 v21, v21, v14, v15
	s_nop 2
	v_max3_f32 v21, v21, v8, v9
	v_max3_f32 v21, v21, v10, v11
	v_pk_mul_f32 v[196:197], v[30:31], v[112:113] op_sel_hi:[1,0]
	ds_bpermute_b32 v31, v165, v21
	v_add_f32_e32 v7, 0, v229
	v_mfma_f32_16x16x32_bf16 v[172:175], v[192:195], v[2:5], v[172:175]
	v_add_f32_e32 v30, v230, v7
	v_add_f32_e32 v7, 0, v55
	v_pk_mul_f32 v[198:199], v[32:33], v[112:113] op_sel_hi:[1,0]
	v_add_f32_e32 v32, v57, v7
	s_waitcnt lgkmcnt(0)
	v_max_f32_e32 v7, v31, v31
	v_mfma_f32_16x16x32_bf16 v[180:183], v[180:183], v[2:5], v[212:215]
	v_max_f32_e32 v7, v21, v7
	ds_bpermute_b32 v21, v166, v7
	v_pk_mul_f32 v[40:41], v[40:41], v[112:113] op_sel_hi:[1,0]
	v_mfma_f32_16x16x32_bf16 v[200:203], v[208:211], v[2:5], v[200:203]
	v_mul_f32_e64 v38, v38, v112
	v_mul_f32_e64 v39, v39, v112
	v_pk_mul_f32 v[36:37], v[36:37], v[112:113] op_sel_hi:[1,0]
	v_pk_mul_f32 v[34:35], v[34:35], v[112:113] op_sel_hi:[1,0]
	v_mfma_f32_16x16x32_bf16 v[2:5], v[184:187], v[2:5], v[16:19]
	v_mul_f32_e64 v28, v28, v112
	v_mul_f32_e64 v29, v29, v112
	v_pk_mul_f32 v[26:27], v[26:27], v[112:113] op_sel_hi:[1,0]
	s_waitcnt lgkmcnt(0)
	v_max3_f32 v113, v228, v7, v21
	v_max3_f32 v16, v172, s70, v173
	v_max3_f32 v16, v16, v174, v175
	v_max3_f32 v16, v16, v180, v181
	v_max3_f32 v16, v16, v182, v183
	v_max3_f32 v16, v16, v200, v201
	v_sub_f32_e32 v7, v176, v113
	v_max3_f32 v16, v16, v202, v203
	v_exp_f32_e32 v149, v7
	v_sub_f32_e32 v7, v177, v113
	v_max3_f32 v16, v16, v2, v3
	v_exp_f32_e32 v131, v7
	v_sub_f32_e32 v7, v178, v113
	v_max3_f32 v16, v16, v4, v5
	v_exp_f32_e32 v135, v7
	v_sub_f32_e32 v7, v179, v113
	ds_bpermute_b32 v17, v165, v16
	v_add_u32_e32 v33, v123, v139
	v_exp_f32_e32 v139, v7
	v_sub_f32_e32 v7, v188, v113
	v_exp_f32_e32 v129, v7
	v_sub_f32_e32 v7, v189, v113
	v_exp_f32_e32 v133, v7
	v_sub_f32_e32 v7, v190, v113
	v_add_u32_e32 v31, v123, v137
	v_exp_f32_e32 v137, v7
	v_sub_f32_e32 v7, v191, v113
	v_mul_f32_e32 v46, v127, v112
	v_add_u32_e32 v112, v123, v141
	v_exp_f32_e32 v141, v7
	v_sub_f32_e32 v7, v12, v113
	s_waitcnt lgkmcnt(0)
	v_max_f32_e32 v12, v17, v17
	v_max_f32_e32 v12, v16, v12
	ds_bpermute_b32 v16, v166, v12
	v_exp_f32_e32 v143, v7
	v_sub_f32_e32 v7, v13, v113
	v_exp_f32_e32 v145, v7
	v_sub_f32_e32 v7, v14, v113
	s_waitcnt lgkmcnt(0)
	v_max3_f32 v12, v51, v12, v16
	v_sub_f32_e32 v14, v172, v12
	v_sub_f32_e32 v13, v51, v12
	v_exp_f32_e32 v51, v14
	v_sub_f32_e32 v14, v173, v12
	v_cvt_pk_bf16_f32 v192, v55, v57
	v_exp_f32_e32 v55, v14
	v_sub_f32_e32 v14, v174, v12
	v_exp_f32_e32 v59, v14
	v_sub_f32_e32 v14, v175, v12
	v_exp_f32_e32 v67, v14
	v_sub_f32_e32 v14, v180, v12
	v_exp_f32_e32 v69, v14
	v_sub_f32_e32 v14, v181, v12
	v_exp_f32_e32 v53, v14
	v_sub_f32_e32 v14, v182, v12
	v_exp_f32_e32 v57, v14
	v_sub_f32_e32 v14, v183, v12
	v_exp_f32_e32 v61, v14
	v_sub_f32_e32 v14, v200, v12
	v_exp_f32_e32 v63, v14
	v_sub_f32_e32 v14, v201, v12
	v_sub_f32_e32 v2, v2, v12
	v_exp_f32_e32 v65, v14
	v_sub_f32_e32 v14, v202, v12
	v_exp_f32_e32 v49, v2
	v_sub_f32_e32 v2, v3, v12
	v_exp_f32_e32 v111, v14
	v_cvt_pk_bf16_f32 v193, v50, v54
	v_cvt_pk_bf16_f32 v194, v58, v66
	v_cvt_pk_bf16_f32 v195, v68, v52
	v_sub_f32_e32 v14, v203, v12
	v_exp_f32_e32 v21, v2
	v_sub_f32_e32 v2, v4, v12
	v_sub_f32_e32 v12, v5, v12
	v_mfma_f32_16x16x32_bf16 v[16:19], v[106:109], v[192:195], v[38:41]
	v_exp_f32_e32 v47, v2
	ds_read_b128 v[176:179], v31 offset:39168
	ds_read_b128 v[180:183], v33 offset:42496
	ds_read_b128 v[184:187], v112 offset:45824
	v_exp_f32_e32 v115, v14
	v_mfma_f32_16x16x32_bf16 v[36:39], v[102:105], v[192:195], v[34:37]
	v_exp_f32_e32 v147, v7
	v_sub_f32_e32 v7, v15, v113
	v_exp_f32_e32 v151, v7
	v_exp_f32_e32 v35, v12
	v_add_u32_e32 v12, v123, v125
	v_mfma_f32_16x16x32_bf16 v[172:175], v[98:101], v[192:195], v[196:199]
	v_exp_f32_e32 v34, v13
	v_sub_f32_e32 v7, v8, v113
	v_exp_f32_e32 v153, v7
	v_mfma_f32_16x16x32_bf16 v[2:5], v[94:97], v[192:195], v[26:29]
	ds_read_b128 v[188:191], v12 offset:35840
	ds_read_b128 v[192:195], v12 offset:35904
	ds_read_b128 v[200:203], v31 offset:39232
	ds_read_b128 v[204:207], v33 offset:42560
	v_mov_b32_e32 v33, v1
	v_pk_add_f32 v[32:33], v[50:51], v[32:33]
	v_cvt_pk_bf16_f32 v26, v56, v60
	v_pk_add_f32 v[32:33], v[54:55], v[32:33]
	v_cvt_pk_bf16_f32 v27, v62, v64
	v_pk_add_f32 v[32:33], v[58:59], v[32:33]
	v_cvt_pk_bf16_f32 v28, v110, v114
	v_pk_add_f32 v[32:33], v[66:67], v[32:33]
	v_cvt_pk_bf16_f32 v29, v48, v20
	v_pk_add_f32 v[32:33], v[68:69], v[32:33]
	v_sub_f32_e32 v7, v9, v113
	v_pk_add_f32 v[32:33], v[52:53], v[32:33]
	v_mfma_f32_16x16x32_bf16 v[36:39], v[86:89], v[26:29], v[36:39]
	v_add_f32_e64 v32, v56, v32
	v_add_f32_e64 v33, v57, v33
	v_cvt_pk_bf16_f32 v196, v51, v55
	v_pk_add_f32 v[32:33], v[60:61], v[32:33]
	v_mfma_f32_16x16x32_bf16 v[16:19], v[90:93], v[26:29], v[16:19]
	v_add_f32_e64 v32, v62, v32
	v_add_f32_e64 v33, v63, v33
	v_cvt_pk_bf16_f32 v197, v59, v67
	v_pk_add_f32 v[32:33], v[64:65], v[32:33]
	v_mfma_f32_16x16x32_bf16 v[172:175], v[82:85], v[26:29], v[172:175]
	v_cvt_pk_bf16_f32 v198, v69, v53
	v_cvt_pk_bf16_f32 v199, v57, v61
	v_exp_f32_e32 v155, v7
	v_mfma_f32_16x16x32_bf16 v[2:5], v[78:81], v[26:29], v[2:5]
	v_mul_f32_e64 v28, v38, v34
	v_mul_f32_e64 v29, v39, v34
	v_pk_mul_f32 v[26:27], v[36:37], v[34:35] op_sel_hi:[1,0]
	v_sub_f32_e32 v7, v10, v113
	v_pk_add_f32 v[32:33], v[110:111], v[32:33]
	v_cvt_pk_bf16_f32 v6, v229, v230
	v_pk_mul_f32 v[18:19], v[18:19], v[34:35] op_sel_hi:[1,0]
	v_pk_mul_f32 v[16:17], v[16:17], v[34:35] op_sel_hi:[1,0]
	s_waitcnt lgkmcnt(6)
	v_mfma_f32_16x16x32_bf16 v[36:39], v[176:179], v[196:199], v[26:29]
	v_mul_f32_e64 v4, v4, v34
	v_mul_f32_e64 v5, v5, v34
	v_pk_mul_f32 v[2:3], v[2:3], v[34:35] op_sel_hi:[1,0]
	v_exp_f32_e32 v127, v7
	v_pk_mul_f32 v[28:29], v[174:175], v[34:35] op_sel_hi:[1,0]
	v_pk_mul_f32 v[26:27], v[172:173], v[34:35] op_sel_hi:[1,0]
	v_cvt_pk_bf16_f32 v7, v148, v130
	v_cvt_pk_bf16_f32 v8, v134, v138
	v_cvt_pk_bf16_f32 v9, v128, v132
	v_pk_add_f32 v[32:33], v[114:115], v[32:33]
	v_mov_b32_e32 v31, v1
	s_waitcnt lgkmcnt(3)
	v_mfma_f32_16x16x32_bf16 v[16:19], v[188:191], v[196:199], v[16:19]
	v_sub_f32_e32 v10, v11, v113
	v_sub_f32_e32 v116, v228, v113
	v_exp_f32_e32 v11, v10
	v_mfma_f32_16x16x32_bf16 v[172:175], v[180:183], v[196:199], v[26:29]
	v_exp_f32_e32 v10, v116
	ds_read_b128 v[208:211], v112 offset:45888
	v_cvt_pk_bf16_f32 v54, v149, v131
	v_mfma_f32_16x16x32_bf16 v[2:5], v[184:187], v[196:199], v[2:5]
	v_cvt_pk_bf16_f32 v198, v49, v21
	v_cvt_pk_bf16_f32 v196, v63, v65
	v_cvt_pk_bf16_f32 v197, v111, v115
	v_mfma_f32_16x16x32_bf16 v[40:43], v[98:101], v[6:9], v[42:45]
	v_cvt_pk_bf16_f32 v199, v47, v35
	v_cvt_pk_bf16_f32 v55, v135, v139
	v_cvt_pk_bf16_f32 v56, v129, v133
	v_pk_add_f32 v[44:45], v[48:49], v[32:33]
	v_pk_add_f32 v[48:49], v[148:149], v[30:31]
	s_waitcnt lgkmcnt(3)
	v_mfma_f32_16x16x32_bf16 v[26:29], v[192:195], v[196:199], v[16:19]
	v_add_f32_e64 v48, v130, v48
	v_add_f32_e64 v49, v131, v49
	v_cvt_pk_bf16_f32 v33, v127, v11
	v_pk_add_f32 v[48:49], v[134:135], v[48:49]
	s_waitcnt lgkmcnt(2)
	v_mfma_f32_16x16x32_bf16 v[16:19], v[200:203], v[196:199], v[36:39]
	v_add_f32_e64 v48, v138, v48
	v_add_f32_e64 v49, v139, v49
	v_cvt_pk_bf16_f32 v57, v137, v141
	v_pk_add_f32 v[48:49], v[128:129], v[48:49]
	v_mfma_f32_16x16x32_bf16 v[36:39], v[106:109], v[6:9], v[74:77]
	v_add_f32_e64 v48, v132, v48
	v_add_f32_e64 v49, v133, v49
	v_cvt_pk_bf16_f32 v30, v143, v145
	v_pk_add_f32 v[48:49], v[136:137], v[48:49]
	v_mfma_f32_16x16x32_bf16 v[70:73], v[102:105], v[6:9], v[70:73]
	v_add_f32_e64 v48, v140, v48
	v_add_f32_e64 v49, v141, v49
	v_cvt_pk_bf16_f32 v31, v147, v151
	v_pk_add_f32 v[48:49], v[142:143], v[48:49]
	v_mfma_f32_16x16x32_bf16 v[6:9], v[94:97], v[6:9], v[22:25]
	v_add_f32_e64 v48, v144, v48
	v_add_f32_e64 v49, v145, v49
	v_cvt_pk_bf16_f32 v32, v153, v155
	v_pk_add_f32 v[48:49], v[146:147], v[48:49]
	v_cvt_pk_bf16_f32 v22, v136, v140
	v_pk_add_f32 v[48:49], v[150:151], v[48:49]
	v_cvt_pk_bf16_f32 v23, v142, v144
	v_pk_add_f32 v[48:49], v[152:153], v[48:49]
	v_cvt_pk_bf16_f32 v24, v146, v150
	v_pk_add_f32 v[48:49], v[154:155], v[48:49]
	v_cvt_pk_bf16_f32 v25, v152, v154
	v_pk_add_f32 v[48:49], v[126:127], v[48:49]
	s_waitcnt lgkmcnt(0)
	v_add_f32_e32 v49, v49, v11
	v_mfma_f32_16x16x32_bf16 v[36:39], v[90:93], v[22:25], v[36:39]
	v_fmac_f32_e32 v49, v48, v10
	ds_bpermute_b32 v48, v165, v49
	s_barrier
	v_mfma_f32_16x16x32_bf16 v[50:53], v[86:89], v[22:25], v[70:73]
	s_waitcnt lgkmcnt(0)
	v_mfma_f32_16x16x32_bf16 v[40:43], v[82:85], v[22:25], v[40:43]
	v_mfma_f32_16x16x32_bf16 v[6:9], v[78:81], v[22:25], v[6:9]
	s_nop 0
	v_mul_f32_e64 v24, v38, v10
	v_mul_f32_e64 v25, v39, v10
	v_pk_mul_f32 v[22:23], v[36:37], v[10:11] op_sel_hi:[1,0]
	s_nop 0
	v_pk_mul_f32 v[38:39], v[52:53], v[10:11] op_sel_hi:[1,0]
	v_pk_mul_f32 v[36:37], v[50:51], v[10:11] op_sel_hi:[1,0]
	v_pk_mul_f32 v[42:43], v[42:43], v[10:11] op_sel_hi:[1,0]
	v_pk_mul_f32 v[40:41], v[40:41], v[10:11] op_sel_hi:[1,0]
	v_pk_mul_f32 v[8:9], v[8:9], v[10:11] op_sel_hi:[1,0]
	v_pk_mul_f32 v[6:7], v[6:7], v[10:11] op_sel_hi:[1,0]
	v_pk_add_f32 v[10:11], v[20:21], v[44:45]
	v_mfma_f32_16x16x32_bf16 v[22:25], v[188:191], v[54:57], v[22:25]
	v_add_f32_e64 v10, v46, v10
	v_add_f32_e64 v11, v47, v11
	v_add_f32_e32 v21, v11, v35
	v_add_f32_e32 v11, v49, v48
	ds_bpermute_b32 v20, v166, v11
	v_mfma_f32_16x16x32_bf16 v[36:39], v[176:179], v[54:57], v[36:39]
	v_fmac_f32_e32 v21, v10, v34
	s_waitcnt lgkmcnt(0)
	v_add_f32_e32 v20, v11, v20
	v_mfma_f32_16x16x32_bf16 v[40:43], v[180:183], v[54:57], v[40:43]
	v_lshl_add_u64 v[10:11], v[120:121], 0, v[0:1]
	v_mfma_f32_16x16x32_bf16 v[6:9], v[184:187], v[54:57], v[6:9]
	v_mfma_f32_16x16x32_bf16 v[22:25], v[192:195], v[30:33], v[22:25]
	v_mfma_f32_16x16x32_bf16 v[36:39], v[200:203], v[30:33], v[36:39]
	v_mfma_f32_16x16x32_bf16 v[40:43], v[204:207], v[30:33], v[40:43]
	v_mfma_f32_16x16x32_bf16 v[6:9], v[208:211], v[30:33], v[6:9]
	v_div_scale_f32 v30, s[2:3], v20, v20, 1.0
	v_rcp_f32_e32 v31, v30
	v_mfma_f32_16x16x32_bf16 v[12:15], v[204:207], v[196:199], v[172:175]
	v_fma_f32 v0, -v30, v31, 1.0
	v_fmac_f32_e32 v31, v0, v31
	v_div_scale_f32 v0, vcc, 1.0, v20, 1.0
	v_mul_f32_e32 v32, v0, v31
	v_fma_f32 v33, -v30, v32, v0
	v_fmac_f32_e32 v32, v33, v31
	v_fma_f32 v0, -v30, v32, v0
	v_div_fmas_f32 v0, v0, v31, v32
	v_mov_b64_e32 v[30:31], s[12:13]
	v_mad_u64_u32 v[30:31], s[2:3], v10, s33, v[30:31]
	v_div_fixup_f32 v20, v0, v20, 1.0
	v_mad_i32_i24 v31, v11, s33, v31
	v_lshlrev_b32_e32 v0, 1, v119
	v_mov_b32_e32 v119, v1
	v_lshl_add_u64 v[10:11], v[30:31], 0, v[0:1]
	v_lshl_add_u64 v[10:11], v[10:11], 0, v[118:119]
	s_mov_b64 s[2:3], 0xa000c00
	ds_bpermute_b32 v0, v165, v21
	v_lshl_add_u64 v[30:31], v[10:11], 0, s[2:3]
	v_pk_mul_f32 v[22:23], v[22:23], v[20:21] op_sel_hi:[1,0]
	v_pk_mul_f32 v[24:25], v[24:25], v[20:21] op_sel_hi:[1,0]
	s_mov_b32 s2, 0xa000000
	v_cvt_pk_bf16_f32 v22, v22, v23
	v_cvt_pk_bf16_f32 v23, v24, v25
	v_add_co_u32_e32 v24, vcc, s2, v10
	s_waitcnt lgkmcnt(0)
	v_add_f32_e32 v0, v21, v0
	v_addc_co_u32_e32 v25, vcc, 0, v11, vcc
	global_store_dwordx2 v[24:25], v[22:23], off offset:3072
	v_pk_mul_f32 v[22:23], v[36:37], v[20:21] op_sel_hi:[1,0]
	v_pk_mul_f32 v[24:25], v[38:39], v[20:21] op_sel_hi:[1,0]
	v_cvt_pk_bf16_f32 v22, v22, v23
	v_cvt_pk_bf16_f32 v23, v24, v25
	global_store_dwordx2 v[30:31], v[22:23], off offset:32
	v_pk_mul_f32 v[22:23], v[40:41], v[20:21] op_sel_hi:[1,0]
	v_pk_mul_f32 v[24:25], v[42:43], v[20:21] op_sel_hi:[1,0]
	ds_bpermute_b32 v21, v166, v0
	v_mfma_f32_16x16x32_bf16 v[2:5], v[208:211], v[196:199], v[2:5]
	v_cvt_pk_bf16_f32 v22, v22, v23
	v_cvt_pk_bf16_f32 v23, v24, v25
	global_store_dwordx2 v[30:31], v[22:23], off offset:64
	s_waitcnt lgkmcnt(0)
	v_add_f32_e32 v0, v0, v21
	v_pk_mul_f32 v[6:7], v[6:7], v[20:21] op_sel_hi:[1,0]
	v_pk_mul_f32 v[8:9], v[8:9], v[20:21] op_sel_hi:[1,0]
	v_div_scale_f32 v20, s[2:3], v0, v0, 1.0
	v_rcp_f32_e32 v21, v20
	v_cvt_pk_bf16_f32 v6, v6, v7
	v_cvt_pk_bf16_f32 v7, v8, v9
	global_store_dwordx2 v[30:31], v[6:7], off offset:96
	v_fma_f32 v6, -v20, v21, 1.0
	v_fmac_f32_e32 v21, v6, v21
	v_div_scale_f32 v6, vcc, 1.0, v0, 1.0
	v_mul_f32_e32 v7, v6, v21
	v_fma_f32 v8, -v20, v7, v6
	v_fmac_f32_e32 v7, v8, v21
	v_fma_f32 v6, -v20, v7, v6
	v_div_fmas_f32 v6, v6, v21, v7
	s_mov_b64 s[2:3], 0xa01e000
	v_div_fixup_f32 v0, v6, v0, 1.0
	v_lshl_add_u64 v[6:7], v[10:11], 0, s[2:3]
	s_mov_b32 s2, 0xa01e000
	v_pk_mul_f32 v[8:9], v[26:27], v[0:1] op_sel_hi:[1,0]
	v_pk_mul_f32 v[20:21], v[28:29], v[0:1] op_sel_hi:[1,0]
	v_add_co_u32_e32 v10, vcc, s2, v10
	v_cvt_pk_bf16_f32 v8, v8, v9
	v_cvt_pk_bf16_f32 v9, v20, v21
	v_addc_co_u32_e32 v11, vcc, 0, v11, vcc
	global_store_dwordx2 v[10:11], v[8:9], off
	v_pk_mul_f32 v[8:9], v[16:17], v[0:1] op_sel_hi:[1,0]
	v_pk_mul_f32 v[10:11], v[18:19], v[0:1] op_sel_hi:[1,0]
	v_cvt_pk_bf16_f32 v8, v8, v9
	v_cvt_pk_bf16_f32 v9, v10, v11
	global_store_dwordx2 v[6:7], v[8:9], off offset:32
	v_pk_mul_f32 v[8:9], v[12:13], v[0:1] op_sel_hi:[1,0]
	v_pk_mul_f32 v[10:11], v[14:15], v[0:1] op_sel_hi:[1,0]
	v_pk_mul_f32 v[2:3], v[2:3], v[0:1] op_sel_hi:[1,0]
	v_pk_mul_f32 v[4:5], v[4:5], v[0:1] op_sel_hi:[1,0]
	v_cvt_pk_bf16_f32 v8, v8, v9
	v_cvt_pk_bf16_f32 v9, v10, v11
	v_cvt_pk_bf16_f32 v2, v2, v3
	v_cvt_pk_bf16_f32 v3, v4, v5
	global_store_dwordx2 v[6:7], v[8:9], off offset:64
	global_store_dwordx2 v[6:7], v[2:3], off offset:96
